# v23 + nt on P0 weight / adaLN-weight row loads (each element read once per launch)
# speedup vs baseline: 1.0034x; 1.0034x over previous
; #define LDS_WAIT() asm volatile("s_waitcnt lgkmcnt(0)" ::: "memory")
; __device__ __forceinline__ void transpose_item(const float* __restrict__ W, int K, int N, bf16* WT, int mode, LAS float* scr, int item, int lane) {
;     const int nblk = N / 32, kb = item / nblk, nb = item % nblk, k0 = 64 * kb, n0 = 32 * nb;
; #pragma unroll 8
;     for (int i = 0; i < 32; ++i) { const int kk = 2 * i + (lane >> 5); scr[kk * 33 + (lane & 31)] = W[(size_t)(k0 + kk) * N + n0 + (lane & 31)]; }
;     LDS_WAIT();
.LBB0_29:
	s_lshl_b32 s12, s6, 1
	s_lshl_b32 s13, s9, 1
	v_add_u32_e32 v78, s12, v46
	v_add_u32_e32 v76, s13, v47
	v_add_u32_e32 v80, s13, v49
	v_add_u32_e32 v82, s12, v48
	v_add_u32_e32 v84, s13, v51
	v_add_u32_e32 v86, s12, v50
	v_add_u32_e32 v88, s13, v53
	v_add_u32_e32 v90, s12, v52
	v_add_u32_e32 v92, s13, v55
	v_add_u32_e32 v94, s12, v54
	v_add_u32_e32 v96, s13, v57
	v_add_u32_e32 v98, s12, v56
	v_add_u32_e32 v100, s13, v59
	v_add_u32_e32 v102, s12, v58
	v_add_u32_e32 v104, s13, v61
	v_add_u32_e32 v106, s12, v60
	v_ashrrev_i32_e32 v79, 31, v78
	v_ashrrev_i32_e32 v77, 31, v76
	v_ashrrev_i32_e32 v83, 31, v82
	v_ashrrev_i32_e32 v81, 31, v80
	v_ashrrev_i32_e32 v87, 31, v86
	v_ashrrev_i32_e32 v85, 31, v84
	v_ashrrev_i32_e32 v91, 31, v90
	v_ashrrev_i32_e32 v89, 31, v88
	v_ashrrev_i32_e32 v95, 31, v94
	v_ashrrev_i32_e32 v93, 31, v92
	v_ashrrev_i32_e32 v99, 31, v98
	v_ashrrev_i32_e32 v97, 31, v96
	v_ashrrev_i32_e32 v103, 31, v102
	v_ashrrev_i32_e32 v101, 31, v100
	v_ashrrev_i32_e32 v107, 31, v106
	v_ashrrev_i32_e32 v105, 31, v104
	v_lshlrev_b64 v[78:79], 12, v[78:79]
	v_lshlrev_b64 v[76:77], 12, v[76:77]
	v_lshlrev_b64 v[80:81], 12, v[80:81]
	v_lshlrev_b64 v[82:83], 12, v[82:83]
	v_lshlrev_b64 v[84:85], 12, v[84:85]
	v_lshlrev_b64 v[86:87], 12, v[86:87]
	v_lshlrev_b64 v[88:89], 12, v[88:89]
	v_lshlrev_b64 v[90:91], 12, v[90:91]
	v_lshlrev_b64 v[92:93], 12, v[92:93]
	v_lshlrev_b64 v[94:95], 12, v[94:95]
	v_lshlrev_b64 v[96:97], 12, v[96:97]
	v_lshlrev_b64 v[98:99], 12, v[98:99]
	v_lshlrev_b64 v[100:101], 12, v[100:101]
	v_lshlrev_b64 v[102:103], 12, v[102:103]
	v_lshlrev_b64 v[104:105], 12, v[104:105]
	v_lshlrev_b64 v[106:107], 12, v[106:107]
	v_lshl_add_u64 v[78:79], v[44:45], 0, v[78:79]
	v_lshl_add_u64 v[76:77], v[44:45], 0, v[76:77]
	v_lshl_add_u64 v[82:83], v[44:45], 0, v[82:83]
	v_lshl_add_u64 v[80:81], v[44:45], 0, v[80:81]
	v_lshl_add_u64 v[86:87], v[44:45], 0, v[86:87]
	v_lshl_add_u64 v[84:85], v[44:45], 0, v[84:85]
	v_lshl_add_u64 v[90:91], v[44:45], 0, v[90:91]
	v_lshl_add_u64 v[88:89], v[44:45], 0, v[88:89]
	v_lshl_add_u64 v[94:95], v[44:45], 0, v[94:95]
	v_lshl_add_u64 v[92:93], v[44:45], 0, v[92:93]
	v_lshl_add_u64 v[98:99], v[44:45], 0, v[98:99]
	v_lshl_add_u64 v[96:97], v[44:45], 0, v[96:97]
	v_lshl_add_u64 v[102:103], v[44:45], 0, v[102:103]
	v_lshl_add_u64 v[100:101], v[44:45], 0, v[100:101]
	v_lshl_add_u64 v[106:107], v[44:45], 0, v[106:107]
	v_lshl_add_u64 v[104:105], v[44:45], 0, v[104:105]
	global_load_dword v75, v[78:79], off nt
	global_load_dword v108, v[76:77], off nt
	global_load_dword v109, v[82:83], off nt
	global_load_dword v110, v[80:81], off nt
	global_load_dword v111, v[86:87], off nt
	global_load_dword v112, v[84:85], off nt
	global_load_dword v113, v[90:91], off nt
	global_load_dword v114, v[88:89], off nt
	global_load_dword v115, v[94:95], off nt
	global_load_dword v116, v[92:93], off nt
	global_load_dword v117, v[98:99], off nt
	global_load_dword v118, v[96:97], off nt
	global_load_dword v119, v[102:103], off nt
	global_load_dword v120, v[100:101], off nt
	global_load_dword v121, v[106:107], off nt
	global_load_dword v122, v[104:105], off nt
	s_add_i32 s6, s6, 16
	s_add_i32 s9, s9, 16
	s_add_i32 s11, s11, -16
	v_add_u32_e32 v76, s12, v0
	v_add_u32_e32 v78, s13, v1
	v_add_u32_e32 v82, s13, v5
	v_add_u32_e32 v80, s12, v2
	v_add_u32_e32 v86, s13, v33
	v_add_u32_e32 v84, s12, v32
	v_add_u32_e32 v90, s13, v35
	v_add_u32_e32 v88, s12, v34
	v_add_u32_e32 v94, s13, v37
	v_add_u32_e32 v92, s12, v36
	v_add_u32_e32 v98, s13, v39
	v_add_u32_e32 v96, s12, v38
	v_add_u32_e32 v102, s13, v41
	v_add_u32_e32 v100, s12, v40
	v_add_u32_e32 v106, s13, v43
	v_add_u32_e32 v104, s12, v42
	s_cmp_lg_u32 s11, 0
	v_mad_u64_u32 v[76:77], s[12:13], v76, s2, v[4:5]
	v_mad_u64_u32 v[78:79], s[12:13], v78, s2, v[4:5]
	v_mad_u64_u32 v[80:81], s[12:13], v80, s2, v[4:5]
	v_mad_u64_u32 v[82:83], s[12:13], v82, s2, v[4:5]
	v_mad_u64_u32 v[84:85], s[12:13], v84, s2, v[4:5]
	v_mad_u64_u32 v[86:87], s[12:13], v86, s2, v[4:5]
	v_mad_u64_u32 v[88:89], s[12:13], v88, s2, v[4:5]
	v_mad_u64_u32 v[90:91], s[12:13], v90, s2, v[4:5]
	v_mad_u64_u32 v[92:93], s[12:13], v92, s2, v[4:5]
	v_mad_u64_u32 v[94:95], s[12:13], v94, s2, v[4:5]
	v_mad_u64_u32 v[96:97], s[12:13], v96, s2, v[4:5]
	v_mad_u64_u32 v[98:99], s[12:13], v98, s2, v[4:5]
	v_mad_u64_u32 v[100:101], s[12:13], v100, s2, v[4:5]
	v_mad_u64_u32 v[102:103], s[12:13], v102, s2, v[4:5]
	v_mad_u64_u32 v[104:105], s[12:13], v104, s2, v[4:5]
	v_mad_u64_u32 v[106:107], s[12:13], v106, s2, v[4:5]
	s_waitcnt vmcnt(15)
	ds_write_b32 v76, v75
	s_waitcnt vmcnt(14)
	ds_write_b32 v78, v108
	s_waitcnt vmcnt(13)
	ds_write_b32 v80, v109
	s_waitcnt vmcnt(12)
	ds_write_b32 v82, v110
	s_waitcnt vmcnt(11)
	ds_write_b32 v84, v111
	s_waitcnt vmcnt(10)
	ds_write_b32 v86, v112
	s_waitcnt vmcnt(9)
	ds_write_b32 v88, v113
	s_waitcnt vmcnt(8)
	ds_write_b32 v90, v114
	s_waitcnt vmcnt(7)
	ds_write_b32 v92, v115
	s_waitcnt vmcnt(6)
	ds_write_b32 v94, v116
	s_waitcnt vmcnt(5)
	ds_write_b32 v96, v117
	s_waitcnt vmcnt(4)
	ds_write_b32 v98, v118
	s_waitcnt vmcnt(3)
	ds_write_b32 v100, v119
	s_waitcnt vmcnt(2)
	ds_write_b32 v102, v120
	s_waitcnt vmcnt(1)
	ds_write_b32 v104, v121
	s_waitcnt vmcnt(0)
	ds_write_b32 v106, v122
	s_cbranch_scc1 .LBB0_29
; #define LAS __attribute__((address_space(3)))
; __device__ __forceinline__ unsigned pk2(float lo, float hi) { f32x2_t v = {lo, hi}; bf16x2_t b = __builtin_convertvector(v, bf16x2_t); return __builtin_bit_cast(unsigned, b); }
; #define LDS_WAIT() asm volatile("s_waitcnt lgkmcnt(0)" ::: "memory")
; __device__ __forceinline__ void transpose_item(const float* __restrict__ W, int K, int N, bf16* WT, int mode, LAS float* scr, int item, int lane) {
;     ...
;     const int c = lane & 7;
; #pragma unroll
;     for (int j = 0; j < 4; ++j) {
;         const int nn = (lane >> 3) + 8 * j; const LAS float* s = scr + (8 * c) * 33 + nn;
;         u32x4 o; o.x = pk2(s[0 * 33], s[1 * 33]); o.y = pk2(s[2 * 33], s[3 * 33]); o.z = pk2(s[4 * 33], s[5 * 33]); o.w = pk2(s[6 * 33], s[7 * 33]);
;         const int n = n0 + nn; const int drow = (mode == 0) ? n : ((n >> 7) * 256 + (mode == 2 ? 128 : 0) + (n & 127));
;         *(u32x4*)(WT + (size_t)drow * K + k0 + 8 * c) = o;
;     }
;     LDS_WAIT();
	s_waitcnt lgkmcnt(0)
	ds_read2_b32 v[48:49], v64 offset0:33 offset1:41
	ds_read2_b32 v[50:51], v64 offset1:8
	ds_read2_b32 v[52:53], v64 offset0:66 offset1:74
	ds_read2_b32 v[54:55], v64 offset0:99 offset1:107
	ds_read2_b32 v[56:57], v64 offset0:132 offset1:140
	ds_read2_b32 v[58:59], v64 offset0:165 offset1:173
	ds_read2_b32 v[60:61], v64 offset0:198 offset1:206
	ds_read2_b32 v[76:77], v64 offset0:231 offset1:239
	s_and_b32 s10, 0xffff, s10
	s_lshl_b32 s6, s8, 1
	v_lshl_add_u64 v[78:79], v[20:21], 0, s[6:7]
	s_waitcnt lgkmcnt(6)
	v_cvt_pk_bf16_f32 v44, v50, v48
	v_add_u32_e32 v48, s10, v63
	s_waitcnt lgkmcnt(4)
	v_cvt_pk_bf16_f32 v45, v52, v54
	s_waitcnt lgkmcnt(2)
	v_cvt_pk_bf16_f32 v46, v56, v58
	s_waitcnt lgkmcnt(0)
	v_cvt_pk_bf16_f32 v47, v60, v76
	v_mad_i64_i32 v[80:81], s[8:9], v48, s34, v[78:79]
	global_store_dwordx4 v[80:81], v[44:47], off
	v_add_u32_e32 v48, s10, v65
	s_mov_b64 s[24:25], 0
	v_cvt_pk_bf16_f32 v44, v51, v49
	v_cvt_pk_bf16_f32 v45, v53, v55
	v_cvt_pk_bf16_f32 v46, v57, v59
	v_cvt_pk_bf16_f32 v47, v61, v77
	ds_read2_b32 v[50:51], v64 offset0:49 offset1:57
	ds_read2_b32 v[52:53], v64 offset0:16 offset1:24
	ds_read2_b32 v[54:55], v64 offset0:82 offset1:90
	ds_read2_b32 v[56:57], v64 offset0:115 offset1:123
	ds_read2_b32 v[58:59], v64 offset0:148 offset1:156
	ds_read2_b32 v[60:61], v64 offset0:181 offset1:189
	ds_read2_b32 v[76:77], v64 offset0:214 offset1:222
	ds_read2_b32 v[80:81], v64 offset0:247 offset1:255
	v_mad_i64_i32 v[48:49], s[8:9], v48, s34, v[78:79]
	global_store_dwordx4 v[48:49], v[44:47], off
	v_add_u32_e32 v48, s10, v66
	v_mad_i64_i32 v[48:49], s[8:9], v48, s34, v[78:79]
	s_waitcnt lgkmcnt(6)
	v_cvt_pk_bf16_f32 v44, v52, v50
	s_waitcnt lgkmcnt(4)
	v_cvt_pk_bf16_f32 v45, v54, v56
	s_waitcnt lgkmcnt(2)
	v_cvt_pk_bf16_f32 v46, v58, v60
	s_waitcnt lgkmcnt(0)
	v_cvt_pk_bf16_f32 v47, v76, v80
	global_store_dwordx4 v[48:49], v[44:47], off
	v_add_u32_e32 v48, s10, v67
	v_mad_i64_i32 v[48:49], s[8:9], v48, s34, v[78:79]
	v_cvt_pk_bf16_f32 v44, v53, v51
	v_cvt_pk_bf16_f32 v45, v55, v57
	v_cvt_pk_bf16_f32 v46, v59, v61
	v_cvt_pk_bf16_f32 v47, v77, v81
	global_store_dwordx4 v[48:49], v[44:47], off
	s_waitcnt lgkmcnt(0)

; #define LDS_WAIT() asm volatile("s_waitcnt lgkmcnt(0)" ::: "memory")
; __device__ __forceinline__ void transpose_item(const float* __restrict__ W, int K, int N, bf16* WT, int mode, LAS float* scr, int item, int lane) {
;     ...
; #pragma unroll 8
;     for (int i = 0; i < 32; ++i) { const int kk = 2 * i + (lane >> 5); scr[kk * 33 + (lane & 31)] = W[(size_t)(k0 + kk) * N + n0 + (lane & 31)]; }
;     LDS_WAIT();
.LBB0_33:
	s_lshl_b32 s14, s10, 1
	s_lshl_b32 s15, s6, 1
	v_add_u32_e32 v76, s14, v46
	v_add_u32_e32 v75, s15, v47
	v_add_u32_e32 v82, s15, v49
	v_add_u32_e32 v80, s14, v48
	v_add_u32_e32 v86, s15, v51
	v_add_u32_e32 v84, s14, v50
	v_add_u32_e32 v90, s15, v53
	v_add_u32_e32 v88, s14, v52
	v_add_u32_e32 v94, s15, v55
	v_add_u32_e32 v92, s14, v54
	v_add_u32_e32 v98, s15, v57
	v_add_u32_e32 v96, s14, v56
	v_add_u32_e32 v102, s15, v59
	v_add_u32_e32 v100, s14, v58
	v_add_u32_e32 v106, s15, v61
	v_add_u32_e32 v104, s14, v60
	v_mad_i64_i32 v[76:77], s[12:13], v76, s36, v[44:45]
	v_mad_i64_i32 v[78:79], s[12:13], v75, s36, v[44:45]
	v_mad_i64_i32 v[80:81], s[12:13], v80, s36, v[44:45]
	v_mad_i64_i32 v[82:83], s[12:13], v82, s36, v[44:45]
	v_mad_i64_i32 v[84:85], s[12:13], v84, s36, v[44:45]
	v_mad_i64_i32 v[86:87], s[12:13], v86, s36, v[44:45]
	v_mad_i64_i32 v[88:89], s[12:13], v88, s36, v[44:45]
	v_mad_i64_i32 v[90:91], s[12:13], v90, s36, v[44:45]
	v_mad_i64_i32 v[92:93], s[12:13], v92, s36, v[44:45]
	v_mad_i64_i32 v[94:95], s[12:13], v94, s36, v[44:45]
	v_mad_i64_i32 v[96:97], s[12:13], v96, s36, v[44:45]
	v_mad_i64_i32 v[98:99], s[12:13], v98, s36, v[44:45]
	v_mad_i64_i32 v[100:101], s[12:13], v100, s36, v[44:45]
	v_mad_i64_i32 v[102:103], s[12:13], v102, s36, v[44:45]
	v_mad_i64_i32 v[104:105], s[12:13], v104, s36, v[44:45]
	v_mad_i64_i32 v[106:107], s[12:13], v106, s36, v[44:45]
	global_load_dword v75, v[76:77], off nt
	global_load_dword v108, v[78:79], off nt
	global_load_dword v109, v[80:81], off nt
	global_load_dword v110, v[82:83], off nt
	global_load_dword v111, v[84:85], off nt
	global_load_dword v112, v[86:87], off nt
	global_load_dword v113, v[88:89], off nt
	global_load_dword v114, v[90:91], off nt
	global_load_dword v115, v[92:93], off nt
	global_load_dword v116, v[94:95], off nt
	global_load_dword v117, v[96:97], off nt
	global_load_dword v118, v[98:99], off nt
	global_load_dword v119, v[100:101], off nt
	global_load_dword v120, v[102:103], off nt
	global_load_dword v121, v[104:105], off nt
	global_load_dword v122, v[106:107], off nt
	s_add_i32 s10, s10, 16
	s_add_i32 s6, s6, 16
	s_add_i32 s11, s11, -16
	v_add_u32_e32 v76, s14, v0
	v_add_u32_e32 v78, s15, v1
	v_add_u32_e32 v82, s15, v5
	v_add_u32_e32 v80, s14, v2
	v_add_u32_e32 v86, s15, v33
	v_add_u32_e32 v84, s14, v32
	v_add_u32_e32 v90, s15, v35
	v_add_u32_e32 v88, s14, v34
	v_add_u32_e32 v94, s15, v37
	v_add_u32_e32 v92, s14, v36
	v_add_u32_e32 v98, s15, v39
	v_add_u32_e32 v96, s14, v38
	v_add_u32_e32 v102, s15, v41
	v_add_u32_e32 v100, s14, v40
	v_add_u32_e32 v106, s15, v43
	v_add_u32_e32 v104, s14, v42
	s_cmp_lg_u32 s11, 0
	v_mad_u64_u32 v[76:77], s[12:13], v76, s2, v[4:5]
	v_mad_u64_u32 v[78:79], s[12:13], v78, s2, v[4:5]
	v_mad_u64_u32 v[80:81], s[12:13], v80, s2, v[4:5]
	v_mad_u64_u32 v[82:83], s[12:13], v82, s2, v[4:5]
	v_mad_u64_u32 v[84:85], s[12:13], v84, s2, v[4:5]
	v_mad_u64_u32 v[86:87], s[12:13], v86, s2, v[4:5]
	v_mad_u64_u32 v[88:89], s[12:13], v88, s2, v[4:5]
	v_mad_u64_u32 v[90:91], s[12:13], v90, s2, v[4:5]
	v_mad_u64_u32 v[92:93], s[12:13], v92, s2, v[4:5]
	v_mad_u64_u32 v[94:95], s[12:13], v94, s2, v[4:5]
	v_mad_u64_u32 v[96:97], s[12:13], v96, s2, v[4:5]
	v_mad_u64_u32 v[98:99], s[12:13], v98, s2, v[4:5]
	v_mad_u64_u32 v[100:101], s[12:13], v100, s2, v[4:5]
	v_mad_u64_u32 v[102:103], s[12:13], v102, s2, v[4:5]
	v_mad_u64_u32 v[104:105], s[12:13], v104, s2, v[4:5]
	v_mad_u64_u32 v[106:107], s[12:13], v106, s2, v[4:5]
	s_waitcnt vmcnt(15)
	ds_write_b32 v76, v75
	s_waitcnt vmcnt(14)
	ds_write_b32 v78, v108
	s_waitcnt vmcnt(13)
	ds_write_b32 v80, v109
	s_waitcnt vmcnt(12)
	ds_write_b32 v82, v110
	s_waitcnt vmcnt(11)
	ds_write_b32 v84, v111
	s_waitcnt vmcnt(10)
	ds_write_b32 v86, v112
	s_waitcnt vmcnt(9)
	ds_write_b32 v88, v113
	s_waitcnt vmcnt(8)
	ds_write_b32 v90, v114
	s_waitcnt vmcnt(7)
	ds_write_b32 v92, v115
	s_waitcnt vmcnt(6)
	ds_write_b32 v94, v116
	s_waitcnt vmcnt(5)
	ds_write_b32 v96, v117
	s_waitcnt vmcnt(4)
	ds_write_b32 v98, v118
	s_waitcnt vmcnt(3)
	ds_write_b32 v100, v119
	s_waitcnt vmcnt(2)
	ds_write_b32 v102, v120
	s_waitcnt vmcnt(1)
	ds_write_b32 v104, v121
	s_waitcnt vmcnt(0)
	ds_write_b32 v106, v122
	s_cbranch_scc1 .LBB0_33
; #define LAS __attribute__((address_space(3)))
; __device__ __forceinline__ unsigned pk2(float lo, float hi) { f32x2_t v = {lo, hi}; bf16x2_t b = __builtin_convertvector(v, bf16x2_t); return __builtin_bit_cast(unsigned, b); }
; #define LDS_WAIT() asm volatile("s_waitcnt lgkmcnt(0)" ::: "memory")
; __device__ __forceinline__ void transpose_item(const float* __restrict__ W, int K, int N, bf16* WT, int mode, LAS float* scr, int item, int lane) {
;     ...
;     const int c = lane & 7;
; #pragma unroll
;     for (int j = 0; j < 4; ++j) {
;         const int nn = (lane >> 3) + 8 * j; const LAS float* s = scr + (8 * c) * 33 + nn;
;         u32x4 o; o.x = pk2(s[0 * 33], s[1 * 33]); o.y = pk2(s[2 * 33], s[3 * 33]); o.z = pk2(s[4 * 33], s[5 * 33]); o.w = pk2(s[6 * 33], s[7 * 33]);
;         const int n = n0 + nn; const int drow = (mode == 0) ? n : ((n >> 7) * 256 + (mode == 2 ? 128 : 0) + (n & 127));
;         *(u32x4*)(WT + (size_t)drow * K + k0 + 8 * c) = o;
;     }
;     LDS_WAIT();
	s_waitcnt lgkmcnt(0)
	s_and_b32 s9, 0xffff, s9
	ds_read2_b32 v[48:49], v64 offset0:33 offset1:41
	ds_read2_b32 v[50:51], v64 offset1:8
	ds_read2_b32 v[52:53], v64 offset0:66 offset1:74
	ds_read2_b32 v[54:55], v64 offset0:99 offset1:107
	ds_read2_b32 v[56:57], v64 offset0:132 offset1:140
	ds_read2_b32 v[58:59], v64 offset0:165 offset1:173
	ds_read2_b32 v[60:61], v64 offset0:198 offset1:206
	ds_read2_b32 v[76:77], v64 offset0:231 offset1:239
	s_waitcnt lgkmcnt(6)
	v_cvt_pk_bf16_f32 v44, v50, v48
	v_add_u32_e32 v48, s9, v63
	v_lshlrev_b32_e32 v50, 1, v48
	v_and_b32_e32 v50, 0xffffff00, v50
	v_and_b32_e32 v48, 0x7f, v48
	s_and_b32 s6, 0xffff, s8
	v_or3_b32 v80, v48, v50, s38
	s_lshl_b32 s6, s6, 1
	v_ashrrev_i32_e32 v81, 31, v80
	v_lshl_add_u64 v[78:79], v[22:23], 0, s[6:7]
	v_lshlrev_b64 v[80:81], 11, v[80:81]
	s_waitcnt lgkmcnt(4)
	v_cvt_pk_bf16_f32 v45, v52, v54
	s_waitcnt lgkmcnt(2)
	v_cvt_pk_bf16_f32 v46, v56, v58
	s_waitcnt lgkmcnt(0)
	v_cvt_pk_bf16_f32 v47, v60, v76
	v_lshl_add_u64 v[80:81], v[78:79], 0, v[80:81]
	v_add_u32_e32 v48, s9, v65
	global_store_dwordx4 v[80:81], v[44:47], off
	s_nop 1
	v_cvt_pk_bf16_f32 v44, v51, v49
	v_lshlrev_b32_e32 v49, 1, v48
	v_and_b32_e32 v49, 0xffffff00, v49
	v_and_b32_e32 v48, 0x7f, v48
	v_or3_b32 v48, v48, v49, s38
	v_ashrrev_i32_e32 v49, 31, v48
	v_lshlrev_b64 v[48:49], 11, v[48:49]
	v_cvt_pk_bf16_f32 v45, v53, v55
	v_cvt_pk_bf16_f32 v46, v57, v59
	v_cvt_pk_bf16_f32 v47, v61, v77
	v_lshl_add_u64 v[48:49], v[78:79], 0, v[48:49]
	ds_read2_b32 v[50:51], v64 offset0:16 offset1:24
	ds_read2_b32 v[52:53], v64 offset0:49 offset1:57
	ds_read2_b32 v[54:55], v64 offset0:82 offset1:90
	ds_read2_b32 v[56:57], v64 offset0:115 offset1:123
	ds_read2_b32 v[58:59], v64 offset0:148 offset1:156
	ds_read2_b32 v[60:61], v64 offset0:181 offset1:189
	ds_read2_b32 v[76:77], v64 offset0:214 offset1:222
	ds_read2_b32 v[80:81], v64 offset0:247 offset1:255
	global_store_dwordx4 v[48:49], v[44:47], off
	v_add_u32_e32 v48, s9, v66
	v_lshlrev_b32_e32 v49, 1, v48
	v_and_b32_e32 v49, 0xffffff00, v49
	v_and_b32_e32 v48, 0x7f, v48
	v_or3_b32 v48, v48, v49, s38
	v_ashrrev_i32_e32 v49, 31, v48
	v_lshlrev_b64 v[48:49], 11, v[48:49]
	s_waitcnt lgkmcnt(6)
	v_cvt_pk_bf16_f32 v44, v50, v52
	s_waitcnt lgkmcnt(4)
	v_cvt_pk_bf16_f32 v45, v54, v56
	s_waitcnt lgkmcnt(2)
	v_cvt_pk_bf16_f32 v46, v58, v60
	s_waitcnt lgkmcnt(0)
	v_cvt_pk_bf16_f32 v47, v76, v80
	v_lshl_add_u64 v[48:49], v[78:79], 0, v[48:49]
	global_store_dwordx4 v[48:49], v[44:47], off
	v_add_u32_e32 v48, s9, v67
	v_lshlrev_b32_e32 v49, 1, v48
	v_and_b32_e32 v49, 0xffffff00, v49
	v_and_b32_e32 v48, 0x7f, v48
	v_or3_b32 v48, v48, v49, s38
	v_ashrrev_i32_e32 v49, 31, v48
	v_lshlrev_b64 v[48:49], 11, v[48:49]
	v_cvt_pk_bf16_f32 v44, v51, v53
	v_cvt_pk_bf16_f32 v45, v55, v57
	v_cvt_pk_bf16_f32 v46, v59, v61
	v_cvt_pk_bf16_f32 v47, v77, v81
	v_lshl_add_u64 v[48:49], v[78:79], 0, v[48:49]
	global_store_dwordx4 v[48:49], v[44:47], off
	s_waitcnt lgkmcnt(0)

; #define LAS __attribute__((address_space(3)))
; __device__ __forceinline__ unsigned pk2(float lo, float hi) { f32x2_t v = {lo, hi}; bf16x2_t b = __builtin_convertvector(v, bf16x2_t); return __builtin_bit_cast(unsigned, b); }
; #define LDS_WAIT() asm volatile("s_waitcnt lgkmcnt(0)" ::: "memory")
; __device__ __forceinline__ void transpose_item(const float* __restrict__ W, int K, int N, bf16* WT, int mode, LAS float* scr, int item, int lane) {
;     ...
; #pragma unroll 8
;     for (int i = 0; i < 32; ++i) { const int kk = 2 * i + (lane >> 5); scr[kk * 33 + (lane & 31)] = W[(size_t)(k0 + kk) * N + n0 + (lane & 31)]; }
;     LDS_WAIT();
;     const int c = lane & 7;
; #pragma unroll
;     for (int j = 0; j < 4; ++j) {
;         const int nn = (lane >> 3) + 8 * j; const LAS float* s = scr + (8 * c) * 33 + nn;
;         u32x4 o; o.x = pk2(s[0 * 33], s[1 * 33]); o.y = pk2(s[2 * 33], s[3 * 33]); o.z = pk2(s[4 * 33], s[5 * 33]); o.w = pk2(s[6 * 33], s[7 * 33]);
;         const int n = n0 + nn; const int drow = (mode == 0) ? n : ((n >> 7) * 256 + (mode == 2 ? 128 : 0) + (n & 127));
;         *(u32x4*)(WT + (size_t)drow * K + k0 + 8 * c) = o;
;     }
;     LDS_WAIT();
.LBB0_38:
	s_lshl_b32 s14, s10, 1
	s_lshl_b32 s15, s6, 1
	v_add_u32_e32 v76, s14, v46
	v_add_u32_e32 v75, s15, v47
	v_add_u32_e32 v82, s15, v49
	v_add_u32_e32 v80, s14, v48
	v_add_u32_e32 v86, s15, v51
	v_add_u32_e32 v84, s14, v50
	v_add_u32_e32 v90, s15, v53
	v_add_u32_e32 v88, s14, v52
	v_add_u32_e32 v94, s15, v55
	v_add_u32_e32 v92, s14, v54
	v_add_u32_e32 v98, s15, v57
	v_add_u32_e32 v96, s14, v56
	v_add_u32_e32 v102, s15, v59
	v_add_u32_e32 v100, s14, v58
	v_add_u32_e32 v106, s15, v61
	v_add_u32_e32 v104, s14, v60
	v_mad_i64_i32 v[76:77], s[12:13], v76, s36, v[44:45]
	v_mad_i64_i32 v[78:79], s[12:13], v75, s36, v[44:45]
	v_mad_i64_i32 v[80:81], s[12:13], v80, s36, v[44:45]
	v_mad_i64_i32 v[82:83], s[12:13], v82, s36, v[44:45]
	v_mad_i64_i32 v[84:85], s[12:13], v84, s36, v[44:45]
	v_mad_i64_i32 v[86:87], s[12:13], v86, s36, v[44:45]
	v_mad_i64_i32 v[88:89], s[12:13], v88, s36, v[44:45]
	v_mad_i64_i32 v[90:91], s[12:13], v90, s36, v[44:45]
	v_mad_i64_i32 v[92:93], s[12:13], v92, s36, v[44:45]
	v_mad_i64_i32 v[94:95], s[12:13], v94, s36, v[44:45]
	v_mad_i64_i32 v[96:97], s[12:13], v96, s36, v[44:45]
	v_mad_i64_i32 v[98:99], s[12:13], v98, s36, v[44:45]
	v_mad_i64_i32 v[100:101], s[12:13], v100, s36, v[44:45]
	v_mad_i64_i32 v[102:103], s[12:13], v102, s36, v[44:45]
	v_mad_i64_i32 v[104:105], s[12:13], v104, s36, v[44:45]
	v_mad_i64_i32 v[106:107], s[12:13], v106, s36, v[44:45]
	global_load_dword v75, v[76:77], off nt
	global_load_dword v108, v[78:79], off nt
	global_load_dword v109, v[80:81], off nt
	global_load_dword v110, v[82:83], off nt
	global_load_dword v111, v[84:85], off nt
	global_load_dword v112, v[86:87], off nt
	global_load_dword v113, v[88:89], off nt
	global_load_dword v114, v[90:91], off nt
	global_load_dword v115, v[92:93], off nt
	global_load_dword v116, v[94:95], off nt
	global_load_dword v117, v[96:97], off nt
	global_load_dword v118, v[98:99], off nt
	global_load_dword v119, v[100:101], off nt
	global_load_dword v120, v[102:103], off nt
	global_load_dword v121, v[104:105], off nt
	global_load_dword v122, v[106:107], off nt
	s_add_i32 s10, s10, 16
	s_add_i32 s6, s6, 16
	s_add_i32 s11, s11, -16
	v_add_u32_e32 v76, s14, v0
	v_add_u32_e32 v78, s15, v1
	v_add_u32_e32 v82, s15, v5
	v_add_u32_e32 v80, s14, v2
	v_add_u32_e32 v86, s15, v33
	v_add_u32_e32 v84, s14, v32
	v_add_u32_e32 v90, s15, v35
	v_add_u32_e32 v88, s14, v34
	v_add_u32_e32 v94, s15, v37
	v_add_u32_e32 v92, s14, v36
	v_add_u32_e32 v98, s15, v39
	v_add_u32_e32 v96, s14, v38
	v_add_u32_e32 v102, s15, v41
	v_add_u32_e32 v100, s14, v40
	v_add_u32_e32 v106, s15, v43
	v_add_u32_e32 v104, s14, v42
	s_cmp_lg_u32 s11, 0
	v_mad_u64_u32 v[76:77], s[12:13], v76, s2, v[4:5]
	v_mad_u64_u32 v[78:79], s[12:13], v78, s2, v[4:5]
	v_mad_u64_u32 v[80:81], s[12:13], v80, s2, v[4:5]
	v_mad_u64_u32 v[82:83], s[12:13], v82, s2, v[4:5]
	v_mad_u64_u32 v[84:85], s[12:13], v84, s2, v[4:5]
	v_mad_u64_u32 v[86:87], s[12:13], v86, s2, v[4:5]
	v_mad_u64_u32 v[88:89], s[12:13], v88, s2, v[4:5]
	v_mad_u64_u32 v[90:91], s[12:13], v90, s2, v[4:5]
	v_mad_u64_u32 v[92:93], s[12:13], v92, s2, v[4:5]
	v_mad_u64_u32 v[94:95], s[12:13], v94, s2, v[4:5]
	v_mad_u64_u32 v[96:97], s[12:13], v96, s2, v[4:5]
	v_mad_u64_u32 v[98:99], s[12:13], v98, s2, v[4:5]
	v_mad_u64_u32 v[100:101], s[12:13], v100, s2, v[4:5]
	v_mad_u64_u32 v[102:103], s[12:13], v102, s2, v[4:5]
	v_mad_u64_u32 v[104:105], s[12:13], v104, s2, v[4:5]
	v_mad_u64_u32 v[106:107], s[12:13], v106, s2, v[4:5]
	s_waitcnt vmcnt(15)
	ds_write_b32 v76, v75
	s_waitcnt vmcnt(14)
	ds_write_b32 v78, v108
	s_waitcnt vmcnt(13)
	ds_write_b32 v80, v109
	s_waitcnt vmcnt(12)
	ds_write_b32 v82, v110
	s_waitcnt vmcnt(11)
	ds_write_b32 v84, v111
	s_waitcnt vmcnt(10)
	ds_write_b32 v86, v112
	s_waitcnt vmcnt(9)
	ds_write_b32 v88, v113
	s_waitcnt vmcnt(8)
	ds_write_b32 v90, v114
	s_waitcnt vmcnt(7)
	ds_write_b32 v92, v115
	s_waitcnt vmcnt(6)
	ds_write_b32 v94, v116
	s_waitcnt vmcnt(5)
	ds_write_b32 v96, v117
	s_waitcnt vmcnt(4)
	ds_write_b32 v98, v118
	s_waitcnt vmcnt(3)
	ds_write_b32 v100, v119
	s_waitcnt vmcnt(2)
	ds_write_b32 v102, v120
	s_waitcnt vmcnt(1)
	ds_write_b32 v104, v121
	s_waitcnt vmcnt(0)
	ds_write_b32 v106, v122
	s_cbranch_scc1 .LBB0_38
	s_waitcnt lgkmcnt(0)
	s_and_b32 s9, 0xffff, s9
	ds_read2_b32 v[48:49], v64 offset0:33 offset1:41
	ds_read2_b32 v[50:51], v64 offset1:8
	ds_read2_b32 v[52:53], v64 offset0:66 offset1:74
	ds_read2_b32 v[54:55], v64 offset0:99 offset1:107
	ds_read2_b32 v[56:57], v64 offset0:132 offset1:140
	ds_read2_b32 v[58:59], v64 offset0:165 offset1:173
	ds_read2_b32 v[60:61], v64 offset0:198 offset1:206
	ds_read2_b32 v[76:77], v64 offset0:231 offset1:239
	s_waitcnt lgkmcnt(6)
	v_cvt_pk_bf16_f32 v44, v50, v48
	v_add_u32_e32 v48, s9, v63
	v_lshlrev_b32_e32 v50, 1, v48
	v_and_b32_e32 v48, 0x7f, v48
	s_and_b32 s6, 0xffff, s8
	v_and_or_b32 v80, v50, s37, v48
	s_lshl_b32 s6, s6, 1
	v_ashrrev_i32_e32 v81, 31, v80
	v_lshl_add_u64 v[78:79], v[22:23], 0, s[6:7]
	v_lshlrev_b64 v[80:81], 11, v[80:81]
	s_waitcnt lgkmcnt(4)
	v_cvt_pk_bf16_f32 v45, v52, v54
	s_waitcnt lgkmcnt(2)
	v_cvt_pk_bf16_f32 v46, v56, v58
	s_waitcnt lgkmcnt(0)
	v_cvt_pk_bf16_f32 v47, v60, v76
	v_lshl_add_u64 v[80:81], v[78:79], 0, v[80:81]
	v_add_u32_e32 v48, s9, v65
	global_store_dwordx4 v[80:81], v[44:47], off
	s_nop 1
	v_cvt_pk_bf16_f32 v44, v51, v49
	v_lshlrev_b32_e32 v49, 1, v48
	v_and_b32_e32 v48, 0x7f, v48
	v_and_or_b32 v48, v49, s37, v48
	v_ashrrev_i32_e32 v49, 31, v48
	v_lshlrev_b64 v[48:49], 11, v[48:49]
	v_cvt_pk_bf16_f32 v45, v53, v55
	v_cvt_pk_bf16_f32 v46, v57, v59
	v_cvt_pk_bf16_f32 v47, v61, v77
	v_lshl_add_u64 v[48:49], v[78:79], 0, v[48:49]
	ds_read2_b32 v[50:51], v64 offset0:16 offset1:24
	ds_read2_b32 v[52:53], v64 offset0:49 offset1:57
	ds_read2_b32 v[54:55], v64 offset0:82 offset1:90
	ds_read2_b32 v[56:57], v64 offset0:115 offset1:123
	ds_read2_b32 v[58:59], v64 offset0:148 offset1:156
	ds_read2_b32 v[60:61], v64 offset0:181 offset1:189
	ds_read2_b32 v[76:77], v64 offset0:214 offset1:222
	ds_read2_b32 v[80:81], v64 offset0:247 offset1:255
	global_store_dwordx4 v[48:49], v[44:47], off
	v_add_u32_e32 v48, s9, v66
	v_lshlrev_b32_e32 v49, 1, v48
	v_and_b32_e32 v48, 0x7f, v48
	v_and_or_b32 v48, v49, s37, v48
	v_ashrrev_i32_e32 v49, 31, v48
	v_lshlrev_b64 v[48:49], 11, v[48:49]
	s_waitcnt lgkmcnt(6)
	v_cvt_pk_bf16_f32 v44, v50, v52
	s_waitcnt lgkmcnt(4)
	v_cvt_pk_bf16_f32 v45, v54, v56
	s_waitcnt lgkmcnt(2)
	v_cvt_pk_bf16_f32 v46, v58, v60
	s_waitcnt lgkmcnt(0)
	v_cvt_pk_bf16_f32 v47, v76, v80
	v_lshl_add_u64 v[48:49], v[78:79], 0, v[48:49]
	global_store_dwordx4 v[48:49], v[44:47], off
	v_add_u32_e32 v48, s9, v67
	v_lshlrev_b32_e32 v49, 1, v48
	v_and_b32_e32 v48, 0x7f, v48
	v_and_or_b32 v48, v49, s37, v48
	v_ashrrev_i32_e32 v49, 31, v48
	v_lshlrev_b64 v[48:49], 11, v[48:49]
	v_cvt_pk_bf16_f32 v44, v51, v53
	v_cvt_pk_bf16_f32 v45, v55, v57
	v_cvt_pk_bf16_f32 v46, v59, v61
	v_cvt_pk_bf16_f32 v47, v77, v81
	v_lshl_add_u64 v[48:49], v[78:79], 0, v[48:49]
	global_store_dwordx4 v[48:49], v[44:47], off
	s_waitcnt lgkmcnt(0)

; #define LDS_WAIT() asm volatile("s_waitcnt lgkmcnt(0)" ::: "memory")
; __device__ __forceinline__ void transpose_item(const float* __restrict__ W, int K, int N, bf16* WT, int mode, LAS float* scr, int item, int lane) {
;     ...
; #pragma unroll 8
;     for (int i = 0; i < 32; ++i) { const int kk = 2 * i + (lane >> 5); scr[kk * 33 + (lane & 31)] = W[(size_t)(k0 + kk) * N + n0 + (lane & 31)]; }
;     LDS_WAIT();
.LBB0_43:
	s_lshl_b32 s12, s6, 1
	s_lshl_b32 s13, s9, 1
	v_add_u32_e32 v78, s12, v46
	v_add_u32_e32 v76, s13, v47
	v_add_u32_e32 v80, s13, v49
	v_add_u32_e32 v82, s12, v48
	v_add_u32_e32 v84, s13, v51
	v_add_u32_e32 v86, s12, v50
	v_add_u32_e32 v88, s13, v53
	v_add_u32_e32 v90, s12, v52
	v_add_u32_e32 v92, s13, v55
	v_add_u32_e32 v94, s12, v54
	v_add_u32_e32 v96, s13, v57
	v_add_u32_e32 v98, s12, v56
	v_add_u32_e32 v100, s13, v59
	v_add_u32_e32 v102, s12, v58
	v_add_u32_e32 v104, s13, v61
	v_add_u32_e32 v106, s12, v60
	v_ashrrev_i32_e32 v79, 31, v78
	v_ashrrev_i32_e32 v77, 31, v76
	v_ashrrev_i32_e32 v83, 31, v82
	v_ashrrev_i32_e32 v81, 31, v80
	v_ashrrev_i32_e32 v87, 31, v86
	v_ashrrev_i32_e32 v85, 31, v84
	v_ashrrev_i32_e32 v91, 31, v90
	v_ashrrev_i32_e32 v89, 31, v88
	v_ashrrev_i32_e32 v95, 31, v94
	v_ashrrev_i32_e32 v93, 31, v92
	v_ashrrev_i32_e32 v99, 31, v98
	v_ashrrev_i32_e32 v97, 31, v96
	v_ashrrev_i32_e32 v103, 31, v102
	v_ashrrev_i32_e32 v101, 31, v100
	v_ashrrev_i32_e32 v107, 31, v106
	v_ashrrev_i32_e32 v105, 31, v104
	v_lshlrev_b64 v[78:79], 12, v[78:79]
	v_lshlrev_b64 v[76:77], 12, v[76:77]
	v_lshlrev_b64 v[80:81], 12, v[80:81]
	v_lshlrev_b64 v[82:83], 12, v[82:83]
	v_lshlrev_b64 v[84:85], 12, v[84:85]
	v_lshlrev_b64 v[86:87], 12, v[86:87]
	v_lshlrev_b64 v[88:89], 12, v[88:89]
	v_lshlrev_b64 v[90:91], 12, v[90:91]
	v_lshlrev_b64 v[92:93], 12, v[92:93]
	v_lshlrev_b64 v[94:95], 12, v[94:95]
	v_lshlrev_b64 v[96:97], 12, v[96:97]
	v_lshlrev_b64 v[98:99], 12, v[98:99]
	v_lshlrev_b64 v[100:101], 12, v[100:101]
	v_lshlrev_b64 v[102:103], 12, v[102:103]
	v_lshlrev_b64 v[104:105], 12, v[104:105]
	v_lshlrev_b64 v[106:107], 12, v[106:107]
	v_lshl_add_u64 v[78:79], v[44:45], 0, v[78:79]
	v_lshl_add_u64 v[76:77], v[44:45], 0, v[76:77]
	v_lshl_add_u64 v[82:83], v[44:45], 0, v[82:83]
	v_lshl_add_u64 v[80:81], v[44:45], 0, v[80:81]
	v_lshl_add_u64 v[86:87], v[44:45], 0, v[86:87]
	v_lshl_add_u64 v[84:85], v[44:45], 0, v[84:85]
	v_lshl_add_u64 v[90:91], v[44:45], 0, v[90:91]
	v_lshl_add_u64 v[88:89], v[44:45], 0, v[88:89]
	v_lshl_add_u64 v[94:95], v[44:45], 0, v[94:95]
	v_lshl_add_u64 v[92:93], v[44:45], 0, v[92:93]
	v_lshl_add_u64 v[98:99], v[44:45], 0, v[98:99]
	v_lshl_add_u64 v[96:97], v[44:45], 0, v[96:97]
	v_lshl_add_u64 v[102:103], v[44:45], 0, v[102:103]
	v_lshl_add_u64 v[100:101], v[44:45], 0, v[100:101]
	v_lshl_add_u64 v[106:107], v[44:45], 0, v[106:107]
	v_lshl_add_u64 v[104:105], v[44:45], 0, v[104:105]
	global_load_dword v75, v[78:79], off nt
	global_load_dword v108, v[76:77], off nt
	global_load_dword v109, v[82:83], off nt
	global_load_dword v110, v[80:81], off nt
	global_load_dword v111, v[86:87], off nt
	global_load_dword v112, v[84:85], off nt
	global_load_dword v113, v[90:91], off nt
	global_load_dword v114, v[88:89], off nt
	global_load_dword v115, v[94:95], off nt
	global_load_dword v116, v[92:93], off nt
	global_load_dword v117, v[98:99], off nt
	global_load_dword v118, v[96:97], off nt
	global_load_dword v119, v[102:103], off nt
	global_load_dword v120, v[100:101], off nt
	global_load_dword v121, v[106:107], off nt
	global_load_dword v122, v[104:105], off nt
	s_add_i32 s6, s6, 16
	s_add_i32 s9, s9, 16
	s_add_i32 s11, s11, -16
	v_add_u32_e32 v76, s12, v0
	v_add_u32_e32 v78, s13, v1
	v_add_u32_e32 v82, s13, v5
	v_add_u32_e32 v80, s12, v2
	v_add_u32_e32 v86, s13, v33
	v_add_u32_e32 v84, s12, v32
	v_add_u32_e32 v90, s13, v35
	v_add_u32_e32 v88, s12, v34
	v_add_u32_e32 v94, s13, v37
	v_add_u32_e32 v92, s12, v36
	v_add_u32_e32 v98, s13, v39
	v_add_u32_e32 v96, s12, v38
	v_add_u32_e32 v102, s13, v41
	v_add_u32_e32 v100, s12, v40
	v_add_u32_e32 v106, s13, v43
	v_add_u32_e32 v104, s12, v42
	s_cmp_lg_u32 s11, 0
	v_mad_u64_u32 v[76:77], s[12:13], v76, s2, v[4:5]
	v_mad_u64_u32 v[78:79], s[12:13], v78, s2, v[4:5]
	v_mad_u64_u32 v[80:81], s[12:13], v80, s2, v[4:5]
	v_mad_u64_u32 v[82:83], s[12:13], v82, s2, v[4:5]
	v_mad_u64_u32 v[84:85], s[12:13], v84, s2, v[4:5]
	v_mad_u64_u32 v[86:87], s[12:13], v86, s2, v[4:5]
	v_mad_u64_u32 v[88:89], s[12:13], v88, s2, v[4:5]
	v_mad_u64_u32 v[90:91], s[12:13], v90, s2, v[4:5]
	v_mad_u64_u32 v[92:93], s[12:13], v92, s2, v[4:5]
	v_mad_u64_u32 v[94:95], s[12:13], v94, s2, v[4:5]
	v_mad_u64_u32 v[96:97], s[12:13], v96, s2, v[4:5]
	v_mad_u64_u32 v[98:99], s[12:13], v98, s2, v[4:5]
	v_mad_u64_u32 v[100:101], s[12:13], v100, s2, v[4:5]
	v_mad_u64_u32 v[102:103], s[12:13], v102, s2, v[4:5]
	v_mad_u64_u32 v[104:105], s[12:13], v104, s2, v[4:5]
	v_mad_u64_u32 v[106:107], s[12:13], v106, s2, v[4:5]
	s_waitcnt vmcnt(15)
	ds_write_b32 v76, v75
	s_waitcnt vmcnt(14)
	ds_write_b32 v78, v108
	s_waitcnt vmcnt(13)
	ds_write_b32 v80, v109
	s_waitcnt vmcnt(12)
	ds_write_b32 v82, v110
	s_waitcnt vmcnt(11)
	ds_write_b32 v84, v111
	s_waitcnt vmcnt(10)
	ds_write_b32 v86, v112
	s_waitcnt vmcnt(9)
	ds_write_b32 v88, v113
	s_waitcnt vmcnt(8)
	ds_write_b32 v90, v114
	s_waitcnt vmcnt(7)
	ds_write_b32 v92, v115
	s_waitcnt vmcnt(6)
	ds_write_b32 v94, v116
	s_waitcnt vmcnt(5)
	ds_write_b32 v96, v117
	s_waitcnt vmcnt(4)
	ds_write_b32 v98, v118
	s_waitcnt vmcnt(3)
	ds_write_b32 v100, v119
	s_waitcnt vmcnt(2)
	ds_write_b32 v102, v120
	s_waitcnt vmcnt(1)
	ds_write_b32 v104, v121
	s_waitcnt vmcnt(0)
	ds_write_b32 v106, v122
	s_cbranch_scc1 .LBB0_43
; #define LAS __attribute__((address_space(3)))
; __device__ __forceinline__ unsigned pk2(float lo, float hi) { f32x2_t v = {lo, hi}; bf16x2_t b = __builtin_convertvector(v, bf16x2_t); return __builtin_bit_cast(unsigned, b); }
; #define LDS_WAIT() asm volatile("s_waitcnt lgkmcnt(0)" ::: "memory")
; __device__ __forceinline__ void transpose_item(const float* __restrict__ W, int K, int N, bf16* WT, int mode, LAS float* scr, int item, int lane) {
;     ...
;     const int c = lane & 7;
; #pragma unroll
;     for (int j = 0; j < 4; ++j) {
;         const int nn = (lane >> 3) + 8 * j; const LAS float* s = scr + (8 * c) * 33 + nn;
;         u32x4 o; o.x = pk2(s[0 * 33], s[1 * 33]); o.y = pk2(s[2 * 33], s[3 * 33]); o.z = pk2(s[4 * 33], s[5 * 33]); o.w = pk2(s[6 * 33], s[7 * 33]);
;         const int n = n0 + nn; const int drow = (mode == 0) ? n : ((n >> 7) * 256 + (mode == 2 ? 128 : 0) + (n & 127));
;         *(u32x4*)(WT + (size_t)drow * K + k0 + 8 * c) = o;
;     }
;     LDS_WAIT();
	s_waitcnt lgkmcnt(0)
	ds_read2_b32 v[48:49], v64 offset0:33 offset1:41
	ds_read2_b32 v[50:51], v64 offset1:8
	ds_read2_b32 v[52:53], v64 offset0:66 offset1:74
	ds_read2_b32 v[54:55], v64 offset0:99 offset1:107
	ds_read2_b32 v[56:57], v64 offset0:132 offset1:140
	ds_read2_b32 v[58:59], v64 offset0:165 offset1:173
	ds_read2_b32 v[60:61], v64 offset0:198 offset1:206
	ds_read2_b32 v[76:77], v64 offset0:231 offset1:239
	s_and_b32 s9, 0xffff, s10
	v_add_u32_e32 v80, s9, v63
	s_lshl_b32 s6, s8, 1
	v_ashrrev_i32_e32 v81, 31, v80
	v_lshl_add_u64 v[78:79], v[24:25], 0, s[6:7]
	v_lshlrev_b64 v[80:81], 11, v[80:81]
	s_waitcnt lgkmcnt(6)
	v_cvt_pk_bf16_f32 v44, v50, v48
	s_waitcnt lgkmcnt(4)
	v_cvt_pk_bf16_f32 v45, v52, v54
	s_waitcnt lgkmcnt(2)
	v_cvt_pk_bf16_f32 v46, v56, v58
	s_waitcnt lgkmcnt(0)
	v_cvt_pk_bf16_f32 v47, v60, v76
	v_lshl_add_u64 v[80:81], v[78:79], 0, v[80:81]
	v_add_u32_e32 v48, s9, v65
	global_store_dwordx4 v[80:81], v[44:47], off
	s_nop 1
	v_cvt_pk_bf16_f32 v44, v51, v49
	v_ashrrev_i32_e32 v49, 31, v48
	v_cvt_pk_bf16_f32 v45, v53, v55
	v_cvt_pk_bf16_f32 v46, v57, v59
	v_cvt_pk_bf16_f32 v47, v61, v77
	v_lshlrev_b64 v[48:49], 11, v[48:49]
	ds_read2_b32 v[50:51], v64 offset0:49 offset1:57
	ds_read2_b32 v[52:53], v64 offset0:16 offset1:24
	ds_read2_b32 v[54:55], v64 offset0:82 offset1:90
	ds_read2_b32 v[56:57], v64 offset0:115 offset1:123
	ds_read2_b32 v[58:59], v64 offset0:148 offset1:156
	ds_read2_b32 v[60:61], v64 offset0:181 offset1:189
	ds_read2_b32 v[76:77], v64 offset0:214 offset1:222
	ds_read2_b32 v[80:81], v64 offset0:247 offset1:255
	v_lshl_add_u64 v[48:49], v[78:79], 0, v[48:49]
	global_store_dwordx4 v[48:49], v[44:47], off
	v_add_u32_e32 v48, s9, v66
	v_ashrrev_i32_e32 v49, 31, v48
	v_lshlrev_b64 v[48:49], 11, v[48:49]
	s_waitcnt lgkmcnt(6)
	v_cvt_pk_bf16_f32 v44, v52, v50
	s_waitcnt lgkmcnt(4)
	v_cvt_pk_bf16_f32 v45, v54, v56
	s_waitcnt lgkmcnt(2)
	v_cvt_pk_bf16_f32 v46, v58, v60
	s_waitcnt lgkmcnt(0)
	v_cvt_pk_bf16_f32 v47, v76, v80
	v_lshl_add_u64 v[48:49], v[78:79], 0, v[48:49]
	global_store_dwordx4 v[48:49], v[44:47], off
	v_add_u32_e32 v48, s9, v67
	v_ashrrev_i32_e32 v49, 31, v48
	v_lshlrev_b64 v[48:49], 11, v[48:49]
	v_cvt_pk_bf16_f32 v44, v53, v51
	v_cvt_pk_bf16_f32 v45, v55, v57
	v_cvt_pk_bf16_f32 v46, v59, v61
	v_cvt_pk_bf16_f32 v47, v77, v81
	v_lshl_add_u64 v[48:49], v[78:79], 0, v[48:49]
	global_store_dwordx4 v[48:49], v[44:47], off
	s_waitcnt lgkmcnt(0)

; #define LDS_WAIT() asm volatile("s_waitcnt lgkmcnt(0)" ::: "memory")
; __device__ __forceinline__ void transpose_item(const float* __restrict__ W, int K, int N, bf16* WT, int mode, LAS float* scr, int item, int lane) {
;     ...
; #pragma unroll 8
;     for (int i = 0; i < 32; ++i) { const int kk = 2 * i + (lane >> 5); scr[kk * 33 + (lane & 31)] = W[(size_t)(k0 + kk) * N + n0 + (lane & 31)]; }
;     LDS_WAIT();
.LBB0_48:
	s_lshl_b32 s12, s6, 1
	s_lshl_b32 s13, s9, 1
	v_add_u32_e32 v78, s12, v46
	v_add_u32_e32 v76, s13, v47
	v_add_u32_e32 v80, s13, v49
	v_add_u32_e32 v82, s12, v48
	v_add_u32_e32 v84, s13, v51
	v_add_u32_e32 v86, s12, v50
	v_add_u32_e32 v88, s13, v53
	v_add_u32_e32 v90, s12, v52
	v_add_u32_e32 v92, s13, v55
	v_add_u32_e32 v94, s12, v54
	v_add_u32_e32 v96, s13, v57
	v_add_u32_e32 v98, s12, v56
	v_add_u32_e32 v100, s13, v59
	v_add_u32_e32 v102, s12, v58
	v_add_u32_e32 v104, s13, v61
	v_add_u32_e32 v106, s12, v60
	v_ashrrev_i32_e32 v79, 31, v78
	v_ashrrev_i32_e32 v77, 31, v76
	v_ashrrev_i32_e32 v83, 31, v82
	v_ashrrev_i32_e32 v81, 31, v80
	v_ashrrev_i32_e32 v87, 31, v86
	v_ashrrev_i32_e32 v85, 31, v84
	v_ashrrev_i32_e32 v91, 31, v90
	v_ashrrev_i32_e32 v89, 31, v88
	v_ashrrev_i32_e32 v95, 31, v94
	v_ashrrev_i32_e32 v93, 31, v92
	v_ashrrev_i32_e32 v99, 31, v98
	v_ashrrev_i32_e32 v97, 31, v96
	v_ashrrev_i32_e32 v103, 31, v102
	v_ashrrev_i32_e32 v101, 31, v100
	v_ashrrev_i32_e32 v107, 31, v106
	v_ashrrev_i32_e32 v105, 31, v104
	v_lshlrev_b64 v[78:79], 12, v[78:79]
	v_lshlrev_b64 v[76:77], 12, v[76:77]
	v_lshlrev_b64 v[80:81], 12, v[80:81]
	v_lshlrev_b64 v[82:83], 12, v[82:83]
	v_lshlrev_b64 v[84:85], 12, v[84:85]
	v_lshlrev_b64 v[86:87], 12, v[86:87]
	v_lshlrev_b64 v[88:89], 12, v[88:89]
	v_lshlrev_b64 v[90:91], 12, v[90:91]
	v_lshlrev_b64 v[92:93], 12, v[92:93]
	v_lshlrev_b64 v[94:95], 12, v[94:95]
	v_lshlrev_b64 v[96:97], 12, v[96:97]
	v_lshlrev_b64 v[98:99], 12, v[98:99]
	v_lshlrev_b64 v[100:101], 12, v[100:101]
	v_lshlrev_b64 v[102:103], 12, v[102:103]
	v_lshlrev_b64 v[104:105], 12, v[104:105]
	v_lshlrev_b64 v[106:107], 12, v[106:107]
	v_lshl_add_u64 v[78:79], v[44:45], 0, v[78:79]
	v_lshl_add_u64 v[76:77], v[44:45], 0, v[76:77]
	v_lshl_add_u64 v[82:83], v[44:45], 0, v[82:83]
	v_lshl_add_u64 v[80:81], v[44:45], 0, v[80:81]
	v_lshl_add_u64 v[86:87], v[44:45], 0, v[86:87]
	v_lshl_add_u64 v[84:85], v[44:45], 0, v[84:85]
	v_lshl_add_u64 v[90:91], v[44:45], 0, v[90:91]
	v_lshl_add_u64 v[88:89], v[44:45], 0, v[88:89]
	v_lshl_add_u64 v[94:95], v[44:45], 0, v[94:95]
	v_lshl_add_u64 v[92:93], v[44:45], 0, v[92:93]
	v_lshl_add_u64 v[98:99], v[44:45], 0, v[98:99]
	v_lshl_add_u64 v[96:97], v[44:45], 0, v[96:97]
	v_lshl_add_u64 v[102:103], v[44:45], 0, v[102:103]
	v_lshl_add_u64 v[100:101], v[44:45], 0, v[100:101]
	v_lshl_add_u64 v[106:107], v[44:45], 0, v[106:107]
	v_lshl_add_u64 v[104:105], v[44:45], 0, v[104:105]
	global_load_dword v75, v[78:79], off nt
	global_load_dword v108, v[76:77], off nt
	global_load_dword v109, v[82:83], off nt
	global_load_dword v110, v[80:81], off nt
	global_load_dword v111, v[86:87], off nt
	global_load_dword v112, v[84:85], off nt
	global_load_dword v113, v[90:91], off nt
	global_load_dword v114, v[88:89], off nt
	global_load_dword v115, v[94:95], off nt
	global_load_dword v116, v[92:93], off nt
	global_load_dword v117, v[98:99], off nt
	global_load_dword v118, v[96:97], off nt
	global_load_dword v119, v[102:103], off nt
	global_load_dword v120, v[100:101], off nt
	global_load_dword v121, v[106:107], off nt
	global_load_dword v122, v[104:105], off nt
	s_add_i32 s6, s6, 16
	s_add_i32 s9, s9, 16
	s_add_i32 s11, s11, -16
	v_add_u32_e32 v76, s12, v0
	v_add_u32_e32 v78, s13, v1
	v_add_u32_e32 v82, s13, v5
	v_add_u32_e32 v80, s12, v2
	v_add_u32_e32 v86, s13, v33
	v_add_u32_e32 v84, s12, v32
	v_add_u32_e32 v90, s13, v35
	v_add_u32_e32 v88, s12, v34
	v_add_u32_e32 v94, s13, v37
	v_add_u32_e32 v92, s12, v36
	v_add_u32_e32 v98, s13, v39
	v_add_u32_e32 v96, s12, v38
	v_add_u32_e32 v102, s13, v41
	v_add_u32_e32 v100, s12, v40
	v_add_u32_e32 v106, s13, v43
	v_add_u32_e32 v104, s12, v42
	s_cmp_lg_u32 s11, 0
	v_mad_u64_u32 v[76:77], s[12:13], v76, s2, v[4:5]
	v_mad_u64_u32 v[78:79], s[12:13], v78, s2, v[4:5]
	v_mad_u64_u32 v[80:81], s[12:13], v80, s2, v[4:5]
	v_mad_u64_u32 v[82:83], s[12:13], v82, s2, v[4:5]
	v_mad_u64_u32 v[84:85], s[12:13], v84, s2, v[4:5]
	v_mad_u64_u32 v[86:87], s[12:13], v86, s2, v[4:5]
	v_mad_u64_u32 v[88:89], s[12:13], v88, s2, v[4:5]
	v_mad_u64_u32 v[90:91], s[12:13], v90, s2, v[4:5]
	v_mad_u64_u32 v[92:93], s[12:13], v92, s2, v[4:5]
	v_mad_u64_u32 v[94:95], s[12:13], v94, s2, v[4:5]
	v_mad_u64_u32 v[96:97], s[12:13], v96, s2, v[4:5]
	v_mad_u64_u32 v[98:99], s[12:13], v98, s2, v[4:5]
	v_mad_u64_u32 v[100:101], s[12:13], v100, s2, v[4:5]
	v_mad_u64_u32 v[102:103], s[12:13], v102, s2, v[4:5]
	v_mad_u64_u32 v[104:105], s[12:13], v104, s2, v[4:5]
	v_mad_u64_u32 v[106:107], s[12:13], v106, s2, v[4:5]
	s_waitcnt vmcnt(15)
	ds_write_b32 v76, v75
	s_waitcnt vmcnt(14)
	ds_write_b32 v78, v108
	s_waitcnt vmcnt(13)
	ds_write_b32 v80, v109
	s_waitcnt vmcnt(12)
	ds_write_b32 v82, v110
	s_waitcnt vmcnt(11)
	ds_write_b32 v84, v111
	s_waitcnt vmcnt(10)
	ds_write_b32 v86, v112
	s_waitcnt vmcnt(9)
	ds_write_b32 v88, v113
	s_waitcnt vmcnt(8)
	ds_write_b32 v90, v114
	s_waitcnt vmcnt(7)
	ds_write_b32 v92, v115
	s_waitcnt vmcnt(6)
	ds_write_b32 v94, v116
	s_waitcnt vmcnt(5)
	ds_write_b32 v96, v117
	s_waitcnt vmcnt(4)
	ds_write_b32 v98, v118
	s_waitcnt vmcnt(3)
	ds_write_b32 v100, v119
	s_waitcnt vmcnt(2)
	ds_write_b32 v102, v120
	s_waitcnt vmcnt(1)
	ds_write_b32 v104, v121
	s_waitcnt vmcnt(0)
	ds_write_b32 v106, v122
	s_cbranch_scc1 .LBB0_48
; #define LAS __attribute__((address_space(3)))
; __device__ __forceinline__ unsigned pk2(float lo, float hi) { f32x2_t v = {lo, hi}; bf16x2_t b = __builtin_convertvector(v, bf16x2_t); return __builtin_bit_cast(unsigned, b); }
; #define LDS_WAIT() asm volatile("s_waitcnt lgkmcnt(0)" ::: "memory")
; __device__ __forceinline__ void transpose_item(const float* __restrict__ W, int K, int N, bf16* WT, int mode, LAS float* scr, int item, int lane) {
;     ...
;     const int c = lane & 7;
; #pragma unroll
;     for (int j = 0; j < 4; ++j) {
;         const int nn = (lane >> 3) + 8 * j; const LAS float* s = scr + (8 * c) * 33 + nn;
;         u32x4 o; o.x = pk2(s[0 * 33], s[1 * 33]); o.y = pk2(s[2 * 33], s[3 * 33]); o.z = pk2(s[4 * 33], s[5 * 33]); o.w = pk2(s[6 * 33], s[7 * 33]);
;         const int n = n0 + nn; const int drow = (mode == 0) ? n : ((n >> 7) * 256 + (mode == 2 ? 128 : 0) + (n & 127));
;         *(u32x4*)(WT + (size_t)drow * K + k0 + 8 * c) = o;
;     }
;     LDS_WAIT();
	s_waitcnt lgkmcnt(0)
	ds_read2_b32 v[48:49], v64 offset0:33 offset1:41
	ds_read2_b32 v[50:51], v64 offset1:8
	ds_read2_b32 v[52:53], v64 offset0:66 offset1:74
	ds_read2_b32 v[54:55], v64 offset0:99 offset1:107
	ds_read2_b32 v[56:57], v64 offset0:132 offset1:140
	ds_read2_b32 v[58:59], v64 offset0:165 offset1:173
	ds_read2_b32 v[60:61], v64 offset0:198 offset1:206
	ds_read2_b32 v[76:77], v64 offset0:231 offset1:239
	s_and_b32 s9, 0xffff, s10
	v_add_u32_e32 v80, s9, v63
	s_lshl_b32 s6, s8, 1
	v_ashrrev_i32_e32 v81, 31, v80
	v_lshl_add_u64 v[78:79], v[26:27], 0, s[6:7]
	v_lshlrev_b64 v[80:81], 10, v[80:81]
	s_waitcnt lgkmcnt(6)
	v_cvt_pk_bf16_f32 v44, v50, v48
	s_waitcnt lgkmcnt(4)
	v_cvt_pk_bf16_f32 v45, v52, v54
	s_waitcnt lgkmcnt(2)
	v_cvt_pk_bf16_f32 v46, v56, v58
	s_waitcnt lgkmcnt(0)
	v_cvt_pk_bf16_f32 v47, v60, v76
	v_lshl_add_u64 v[80:81], v[78:79], 0, v[80:81]
	v_add_u32_e32 v48, s9, v65
	global_store_dwordx4 v[80:81], v[44:47], off
	s_nop 1
	v_cvt_pk_bf16_f32 v44, v51, v49
	v_ashrrev_i32_e32 v49, 31, v48
	v_cvt_pk_bf16_f32 v45, v53, v55
	v_cvt_pk_bf16_f32 v46, v57, v59
	v_cvt_pk_bf16_f32 v47, v61, v77
	v_lshlrev_b64 v[48:49], 10, v[48:49]
	ds_read2_b32 v[50:51], v64 offset0:49 offset1:57
	ds_read2_b32 v[52:53], v64 offset0:16 offset1:24
	ds_read2_b32 v[54:55], v64 offset0:82 offset1:90
	ds_read2_b32 v[56:57], v64 offset0:115 offset1:123
	ds_read2_b32 v[58:59], v64 offset0:148 offset1:156
	ds_read2_b32 v[60:61], v64 offset0:181 offset1:189
	ds_read2_b32 v[76:77], v64 offset0:214 offset1:222
	ds_read2_b32 v[80:81], v64 offset0:247 offset1:255
	v_lshl_add_u64 v[48:49], v[78:79], 0, v[48:49]
	global_store_dwordx4 v[48:49], v[44:47], off
	v_add_u32_e32 v48, s9, v66
	v_ashrrev_i32_e32 v49, 31, v48
	v_lshlrev_b64 v[48:49], 10, v[48:49]
	s_waitcnt lgkmcnt(6)
	v_cvt_pk_bf16_f32 v44, v52, v50
	s_waitcnt lgkmcnt(4)
	v_cvt_pk_bf16_f32 v45, v54, v56
	s_waitcnt lgkmcnt(2)
	v_cvt_pk_bf16_f32 v46, v58, v60
	s_waitcnt lgkmcnt(0)
	v_cvt_pk_bf16_f32 v47, v76, v80
	v_lshl_add_u64 v[48:49], v[78:79], 0, v[48:49]
	global_store_dwordx4 v[48:49], v[44:47], off
	v_add_u32_e32 v48, s9, v67
	v_ashrrev_i32_e32 v49, 31, v48
	v_lshlrev_b64 v[48:49], 10, v[48:49]
	v_cvt_pk_bf16_f32 v44, v53, v51
	v_cvt_pk_bf16_f32 v45, v55, v57
	v_cvt_pk_bf16_f32 v46, v59, v61
	v_cvt_pk_bf16_f32 v47, v77, v81
	v_lshl_add_u64 v[48:49], v[78:79], 0, v[48:49]
	global_store_dwordx4 v[48:49], v[44:47], off
	s_waitcnt lgkmcnt(0)

; #define LDS_WAIT() asm volatile("s_waitcnt lgkmcnt(0)" ::: "memory")
; __device__ __forceinline__ void transpose_item(const float* __restrict__ W, int K, int N, bf16* WT, int mode, LAS float* scr, int item, int lane) {
;     ...
; #pragma unroll 8
;     for (int i = 0; i < 32; ++i) { const int kk = 2 * i + (lane >> 5); scr[kk * 33 + (lane & 31)] = W[(size_t)(k0 + kk) * N + n0 + (lane & 31)]; }
;     LDS_WAIT();
.LBB0_53:
	s_lshl_b32 s12, s6, 1
	s_lshl_b32 s13, s9, 1
	v_add_u32_e32 v78, s12, v46
	v_add_u32_e32 v76, s13, v47
	v_add_u32_e32 v80, s13, v49
	v_add_u32_e32 v82, s12, v48
	v_add_u32_e32 v84, s13, v51
	v_add_u32_e32 v86, s12, v50
	v_add_u32_e32 v88, s13, v53
	v_add_u32_e32 v90, s12, v52
	v_add_u32_e32 v92, s13, v55
	v_add_u32_e32 v94, s12, v54
	v_add_u32_e32 v96, s13, v57
	v_add_u32_e32 v98, s12, v56
	v_add_u32_e32 v100, s13, v59
	v_add_u32_e32 v102, s12, v58
	v_add_u32_e32 v104, s13, v61
	v_add_u32_e32 v106, s12, v60
	v_ashrrev_i32_e32 v79, 31, v78
	v_ashrrev_i32_e32 v77, 31, v76
	v_ashrrev_i32_e32 v83, 31, v82
	v_ashrrev_i32_e32 v81, 31, v80
	v_ashrrev_i32_e32 v87, 31, v86
	v_ashrrev_i32_e32 v85, 31, v84
	v_ashrrev_i32_e32 v91, 31, v90
	v_ashrrev_i32_e32 v89, 31, v88
	v_ashrrev_i32_e32 v95, 31, v94
	v_ashrrev_i32_e32 v93, 31, v92
	v_ashrrev_i32_e32 v99, 31, v98
	v_ashrrev_i32_e32 v97, 31, v96
	v_ashrrev_i32_e32 v103, 31, v102
	v_ashrrev_i32_e32 v101, 31, v100
	v_ashrrev_i32_e32 v107, 31, v106
	v_ashrrev_i32_e32 v105, 31, v104
	v_lshlrev_b64 v[78:79], 12, v[78:79]
	v_lshlrev_b64 v[76:77], 12, v[76:77]
	v_lshlrev_b64 v[80:81], 12, v[80:81]
	v_lshlrev_b64 v[82:83], 12, v[82:83]
	v_lshlrev_b64 v[84:85], 12, v[84:85]
	v_lshlrev_b64 v[86:87], 12, v[86:87]
	v_lshlrev_b64 v[88:89], 12, v[88:89]
	v_lshlrev_b64 v[90:91], 12, v[90:91]
	v_lshlrev_b64 v[92:93], 12, v[92:93]
	v_lshlrev_b64 v[94:95], 12, v[94:95]
	v_lshlrev_b64 v[96:97], 12, v[96:97]
	v_lshlrev_b64 v[98:99], 12, v[98:99]
	v_lshlrev_b64 v[100:101], 12, v[100:101]
	v_lshlrev_b64 v[102:103], 12, v[102:103]
	v_lshlrev_b64 v[104:105], 12, v[104:105]
	v_lshlrev_b64 v[106:107], 12, v[106:107]
	v_lshl_add_u64 v[78:79], v[44:45], 0, v[78:79]
	v_lshl_add_u64 v[76:77], v[44:45], 0, v[76:77]
	v_lshl_add_u64 v[82:83], v[44:45], 0, v[82:83]
	v_lshl_add_u64 v[80:81], v[44:45], 0, v[80:81]
	v_lshl_add_u64 v[86:87], v[44:45], 0, v[86:87]
	v_lshl_add_u64 v[84:85], v[44:45], 0, v[84:85]
	v_lshl_add_u64 v[90:91], v[44:45], 0, v[90:91]
	v_lshl_add_u64 v[88:89], v[44:45], 0, v[88:89]
	v_lshl_add_u64 v[94:95], v[44:45], 0, v[94:95]
	v_lshl_add_u64 v[92:93], v[44:45], 0, v[92:93]
	v_lshl_add_u64 v[98:99], v[44:45], 0, v[98:99]
	v_lshl_add_u64 v[96:97], v[44:45], 0, v[96:97]
	v_lshl_add_u64 v[102:103], v[44:45], 0, v[102:103]
	v_lshl_add_u64 v[100:101], v[44:45], 0, v[100:101]
	v_lshl_add_u64 v[106:107], v[44:45], 0, v[106:107]
	v_lshl_add_u64 v[104:105], v[44:45], 0, v[104:105]
	global_load_dword v75, v[78:79], off nt
	global_load_dword v108, v[76:77], off nt
	global_load_dword v109, v[82:83], off nt
	global_load_dword v110, v[80:81], off nt
	global_load_dword v111, v[86:87], off nt
	global_load_dword v112, v[84:85], off nt
	global_load_dword v113, v[90:91], off nt
	global_load_dword v114, v[88:89], off nt
	global_load_dword v115, v[94:95], off nt
	global_load_dword v116, v[92:93], off nt
	global_load_dword v117, v[98:99], off nt
	global_load_dword v118, v[96:97], off nt
	global_load_dword v119, v[102:103], off nt
	global_load_dword v120, v[100:101], off nt
	global_load_dword v121, v[106:107], off nt
	global_load_dword v122, v[104:105], off nt
	s_add_i32 s6, s6, 16
	s_add_i32 s9, s9, 16
	s_add_i32 s11, s11, -16
	v_add_u32_e32 v76, s12, v0
	v_add_u32_e32 v78, s13, v1
	v_add_u32_e32 v82, s13, v5
	v_add_u32_e32 v80, s12, v2
	v_add_u32_e32 v86, s13, v33
	v_add_u32_e32 v84, s12, v32
	v_add_u32_e32 v90, s13, v35
	v_add_u32_e32 v88, s12, v34
	v_add_u32_e32 v94, s13, v37
	v_add_u32_e32 v92, s12, v36
	v_add_u32_e32 v98, s13, v39
	v_add_u32_e32 v96, s12, v38
	v_add_u32_e32 v102, s13, v41
	v_add_u32_e32 v100, s12, v40
	v_add_u32_e32 v106, s13, v43
	v_add_u32_e32 v104, s12, v42
	s_cmp_lg_u32 s11, 0
	v_mad_u64_u32 v[76:77], s[12:13], v76, s2, v[4:5]
	v_mad_u64_u32 v[78:79], s[12:13], v78, s2, v[4:5]
	v_mad_u64_u32 v[80:81], s[12:13], v80, s2, v[4:5]
	v_mad_u64_u32 v[82:83], s[12:13], v82, s2, v[4:5]
	v_mad_u64_u32 v[84:85], s[12:13], v84, s2, v[4:5]
	v_mad_u64_u32 v[86:87], s[12:13], v86, s2, v[4:5]
	v_mad_u64_u32 v[88:89], s[12:13], v88, s2, v[4:5]
	v_mad_u64_u32 v[90:91], s[12:13], v90, s2, v[4:5]
	v_mad_u64_u32 v[92:93], s[12:13], v92, s2, v[4:5]
	v_mad_u64_u32 v[94:95], s[12:13], v94, s2, v[4:5]
	v_mad_u64_u32 v[96:97], s[12:13], v96, s2, v[4:5]
	v_mad_u64_u32 v[98:99], s[12:13], v98, s2, v[4:5]
	v_mad_u64_u32 v[100:101], s[12:13], v100, s2, v[4:5]
	v_mad_u64_u32 v[102:103], s[12:13], v102, s2, v[4:5]
	v_mad_u64_u32 v[104:105], s[12:13], v104, s2, v[4:5]
	v_mad_u64_u32 v[106:107], s[12:13], v106, s2, v[4:5]
	s_waitcnt vmcnt(15)
	ds_write_b32 v76, v75
	s_waitcnt vmcnt(14)
	ds_write_b32 v78, v108
	s_waitcnt vmcnt(13)
	ds_write_b32 v80, v109
	s_waitcnt vmcnt(12)
	ds_write_b32 v82, v110
	s_waitcnt vmcnt(11)
	ds_write_b32 v84, v111
	s_waitcnt vmcnt(10)
	ds_write_b32 v86, v112
	s_waitcnt vmcnt(9)
	ds_write_b32 v88, v113
	s_waitcnt vmcnt(8)
	ds_write_b32 v90, v114
	s_waitcnt vmcnt(7)
	ds_write_b32 v92, v115
	s_waitcnt vmcnt(6)
	ds_write_b32 v94, v116
	s_waitcnt vmcnt(5)
	ds_write_b32 v96, v117
	s_waitcnt vmcnt(4)
	ds_write_b32 v98, v118
	s_waitcnt vmcnt(3)
	ds_write_b32 v100, v119
	s_waitcnt vmcnt(2)
	ds_write_b32 v102, v120
	s_waitcnt vmcnt(1)
	ds_write_b32 v104, v121
	s_waitcnt vmcnt(0)
	ds_write_b32 v106, v122
	s_cbranch_scc1 .LBB0_53
; #define LAS __attribute__((address_space(3)))
; __device__ __forceinline__ unsigned pk2(float lo, float hi) { f32x2_t v = {lo, hi}; bf16x2_t b = __builtin_convertvector(v, bf16x2_t); return __builtin_bit_cast(unsigned, b); }
; #define LDS_WAIT() asm volatile("s_waitcnt lgkmcnt(0)" ::: "memory")
; __device__ __forceinline__ void transpose_item(const float* __restrict__ W, int K, int N, bf16* WT, int mode, LAS float* scr, int item, int lane) {
;     ...
;     const int c = lane & 7;
; #pragma unroll
;     for (int j = 0; j < 4; ++j) {
;         const int nn = (lane >> 3) + 8 * j; const LAS float* s = scr + (8 * c) * 33 + nn;
;         u32x4 o; o.x = pk2(s[0 * 33], s[1 * 33]); o.y = pk2(s[2 * 33], s[3 * 33]); o.z = pk2(s[4 * 33], s[5 * 33]); o.w = pk2(s[6 * 33], s[7 * 33]);
;         const int n = n0 + nn; const int drow = (mode == 0) ? n : ((n >> 7) * 256 + (mode == 2 ? 128 : 0) + (n & 127));
;         *(u32x4*)(WT + (size_t)drow * K + k0 + 8 * c) = o;
;     }
;     LDS_WAIT();
	s_waitcnt lgkmcnt(0)
	ds_read2_b32 v[48:49], v64 offset0:33 offset1:41
	ds_read2_b32 v[50:51], v64 offset1:8
	ds_read2_b32 v[52:53], v64 offset0:66 offset1:74
	ds_read2_b32 v[54:55], v64 offset0:99 offset1:107
	ds_read2_b32 v[56:57], v64 offset0:132 offset1:140
	ds_read2_b32 v[58:59], v64 offset0:165 offset1:173
	ds_read2_b32 v[60:61], v64 offset0:198 offset1:206
	ds_read2_b32 v[76:77], v64 offset0:231 offset1:239
	s_and_b32 s9, 0xffff, s10
	v_add_u32_e32 v80, s9, v63
	s_lshl_b32 s6, s8, 1
	v_ashrrev_i32_e32 v81, 31, v80
	v_lshl_add_u64 v[78:79], v[28:29], 0, s[6:7]
	v_lshlrev_b64 v[80:81], 10, v[80:81]
	s_waitcnt lgkmcnt(6)
	v_cvt_pk_bf16_f32 v44, v50, v48
	s_waitcnt lgkmcnt(4)
	v_cvt_pk_bf16_f32 v45, v52, v54
	s_waitcnt lgkmcnt(2)
	v_cvt_pk_bf16_f32 v46, v56, v58
	s_waitcnt lgkmcnt(0)
	v_cvt_pk_bf16_f32 v47, v60, v76
	v_lshl_add_u64 v[80:81], v[78:79], 0, v[80:81]
	v_add_u32_e32 v48, s9, v65
	global_store_dwordx4 v[80:81], v[44:47], off
	s_nop 1
	v_cvt_pk_bf16_f32 v44, v51, v49
	v_ashrrev_i32_e32 v49, 31, v48
	v_cvt_pk_bf16_f32 v45, v53, v55
	v_cvt_pk_bf16_f32 v46, v57, v59
	v_cvt_pk_bf16_f32 v47, v61, v77
	v_lshlrev_b64 v[48:49], 10, v[48:49]
	ds_read2_b32 v[50:51], v64 offset0:49 offset1:57
	ds_read2_b32 v[52:53], v64 offset0:16 offset1:24
	ds_read2_b32 v[54:55], v64 offset0:82 offset1:90
	ds_read2_b32 v[56:57], v64 offset0:115 offset1:123
	ds_read2_b32 v[58:59], v64 offset0:148 offset1:156
	ds_read2_b32 v[60:61], v64 offset0:181 offset1:189
	ds_read2_b32 v[76:77], v64 offset0:214 offset1:222
	ds_read2_b32 v[80:81], v64 offset0:247 offset1:255
	v_lshl_add_u64 v[48:49], v[78:79], 0, v[48:49]
	global_store_dwordx4 v[48:49], v[44:47], off
	v_add_u32_e32 v48, s9, v66
	v_ashrrev_i32_e32 v49, 31, v48
	v_lshlrev_b64 v[48:49], 10, v[48:49]
	s_waitcnt lgkmcnt(6)
	v_cvt_pk_bf16_f32 v44, v52, v50
	s_waitcnt lgkmcnt(4)
	v_cvt_pk_bf16_f32 v45, v54, v56
	s_waitcnt lgkmcnt(2)
	v_cvt_pk_bf16_f32 v46, v58, v60
	s_waitcnt lgkmcnt(0)
	v_cvt_pk_bf16_f32 v47, v76, v80
	v_lshl_add_u64 v[48:49], v[78:79], 0, v[48:49]
	global_store_dwordx4 v[48:49], v[44:47], off
	v_add_u32_e32 v48, s9, v67
	v_ashrrev_i32_e32 v49, 31, v48
	v_lshlrev_b64 v[48:49], 10, v[48:49]
	v_cvt_pk_bf16_f32 v44, v53, v51
	v_cvt_pk_bf16_f32 v45, v55, v57
	v_cvt_pk_bf16_f32 v46, v59, v61
	v_cvt_pk_bf16_f32 v47, v77, v81
	v_lshl_add_u64 v[48:49], v[78:79], 0, v[48:49]
	global_store_dwordx4 v[48:49], v[44:47], off
	s_waitcnt lgkmcnt(0)

; #define LAS __attribute__((address_space(3)))
; __device__ __forceinline__ unsigned pk2(float lo, float hi) { f32x2_t v = {lo, hi}; bf16x2_t b = __builtin_convertvector(v, bf16x2_t); return __builtin_bit_cast(unsigned, b); }
; #define LDS_WAIT() asm volatile("s_waitcnt lgkmcnt(0)" ::: "memory")
; __device__ __forceinline__ void transpose_item(const float* __restrict__ W, int K, int N, bf16* WT, int mode, LAS float* scr, int item, int lane) {
;     ...
; #pragma unroll 8
;     for (int i = 0; i < 32; ++i) { const int kk = 2 * i + (lane >> 5); scr[kk * 33 + (lane & 31)] = W[(size_t)(k0 + kk) * N + n0 + (lane & 31)]; }
;     LDS_WAIT();
;     const int c = lane & 7;
; #pragma unroll
;     for (int j = 0; j < 4; ++j) {
;         const int nn = (lane >> 3) + 8 * j; const LAS float* s = scr + (8 * c) * 33 + nn;
;         u32x4 o; o.x = pk2(s[0 * 33], s[1 * 33]); o.y = pk2(s[2 * 33], s[3 * 33]); o.z = pk2(s[4 * 33], s[5 * 33]); o.w = pk2(s[6 * 33], s[7 * 33]);
;         const int n = n0 + nn; const int drow = (mode == 0) ? n : ((n >> 7) * 256 + (mode == 2 ? 128 : 0) + (n & 127));
;         *(u32x4*)(WT + (size_t)drow * K + k0 + 8 * c) = o;
;     }
;     LDS_WAIT();
.LBB0_58:
	s_lshl_b32 s14, s10, 1
	s_lshl_b32 s15, s6, 1
	v_add_u32_e32 v76, s14, v46
	v_add_u32_e32 v75, s15, v47
	v_add_u32_e32 v82, s15, v49
	v_add_u32_e32 v80, s14, v48
	v_add_u32_e32 v86, s15, v51
	v_add_u32_e32 v84, s14, v50
	v_add_u32_e32 v90, s15, v53
	v_add_u32_e32 v88, s14, v52
	v_add_u32_e32 v94, s15, v55
	v_add_u32_e32 v92, s14, v54
	v_add_u32_e32 v98, s15, v57
	v_add_u32_e32 v96, s14, v56
	v_add_u32_e32 v102, s15, v59
	v_add_u32_e32 v100, s14, v58
	v_add_u32_e32 v106, s15, v61
	v_add_u32_e32 v104, s14, v60
	v_mad_i64_i32 v[76:77], s[12:13], v76, s39, v[44:45]
	v_mad_i64_i32 v[78:79], s[12:13], v75, s39, v[44:45]
	v_mad_i64_i32 v[80:81], s[12:13], v80, s39, v[44:45]
	v_mad_i64_i32 v[82:83], s[12:13], v82, s39, v[44:45]
	v_mad_i64_i32 v[84:85], s[12:13], v84, s39, v[44:45]
	v_mad_i64_i32 v[86:87], s[12:13], v86, s39, v[44:45]
	v_mad_i64_i32 v[88:89], s[12:13], v88, s39, v[44:45]
	v_mad_i64_i32 v[90:91], s[12:13], v90, s39, v[44:45]
	v_mad_i64_i32 v[92:93], s[12:13], v92, s39, v[44:45]
	v_mad_i64_i32 v[94:95], s[12:13], v94, s39, v[44:45]
	v_mad_i64_i32 v[96:97], s[12:13], v96, s39, v[44:45]
	v_mad_i64_i32 v[98:99], s[12:13], v98, s39, v[44:45]
	v_mad_i64_i32 v[100:101], s[12:13], v100, s39, v[44:45]
	v_mad_i64_i32 v[102:103], s[12:13], v102, s39, v[44:45]
	v_mad_i64_i32 v[104:105], s[12:13], v104, s39, v[44:45]
	v_mad_i64_i32 v[106:107], s[12:13], v106, s39, v[44:45]
	global_load_dword v75, v[76:77], off nt
	global_load_dword v108, v[78:79], off nt
	global_load_dword v109, v[80:81], off nt
	global_load_dword v110, v[82:83], off nt
	global_load_dword v111, v[84:85], off nt
	global_load_dword v112, v[86:87], off nt
	global_load_dword v113, v[88:89], off nt
	global_load_dword v114, v[90:91], off nt
	global_load_dword v115, v[92:93], off nt
	global_load_dword v116, v[94:95], off nt
	global_load_dword v117, v[96:97], off nt
	global_load_dword v118, v[98:99], off nt
	global_load_dword v119, v[100:101], off nt
	global_load_dword v120, v[102:103], off nt
	global_load_dword v121, v[104:105], off nt
	global_load_dword v122, v[106:107], off nt
	s_add_i32 s10, s10, 16
	s_add_i32 s6, s6, 16
	s_add_i32 s11, s11, -16
	v_add_u32_e32 v76, s14, v0
	v_add_u32_e32 v78, s15, v1
	v_add_u32_e32 v82, s15, v5
	v_add_u32_e32 v80, s14, v2
	v_add_u32_e32 v86, s15, v33
	v_add_u32_e32 v84, s14, v32
	v_add_u32_e32 v90, s15, v35
	v_add_u32_e32 v88, s14, v34
	v_add_u32_e32 v94, s15, v37
	v_add_u32_e32 v92, s14, v36
	v_add_u32_e32 v98, s15, v39
	v_add_u32_e32 v96, s14, v38
	v_add_u32_e32 v102, s15, v41
	v_add_u32_e32 v100, s14, v40
	v_add_u32_e32 v106, s15, v43
	v_add_u32_e32 v104, s14, v42
	s_cmp_lg_u32 s11, 0
	v_mad_u64_u32 v[76:77], s[12:13], v76, s2, v[4:5]
	v_mad_u64_u32 v[78:79], s[12:13], v78, s2, v[4:5]
	v_mad_u64_u32 v[80:81], s[12:13], v80, s2, v[4:5]
	v_mad_u64_u32 v[82:83], s[12:13], v82, s2, v[4:5]
	v_mad_u64_u32 v[84:85], s[12:13], v84, s2, v[4:5]
	v_mad_u64_u32 v[86:87], s[12:13], v86, s2, v[4:5]
	v_mad_u64_u32 v[88:89], s[12:13], v88, s2, v[4:5]
	v_mad_u64_u32 v[90:91], s[12:13], v90, s2, v[4:5]
	v_mad_u64_u32 v[92:93], s[12:13], v92, s2, v[4:5]
	v_mad_u64_u32 v[94:95], s[12:13], v94, s2, v[4:5]
	v_mad_u64_u32 v[96:97], s[12:13], v96, s2, v[4:5]
	v_mad_u64_u32 v[98:99], s[12:13], v98, s2, v[4:5]
	v_mad_u64_u32 v[100:101], s[12:13], v100, s2, v[4:5]
	v_mad_u64_u32 v[102:103], s[12:13], v102, s2, v[4:5]
	v_mad_u64_u32 v[104:105], s[12:13], v104, s2, v[4:5]
	v_mad_u64_u32 v[106:107], s[12:13], v106, s2, v[4:5]
	s_waitcnt vmcnt(15)
	ds_write_b32 v76, v75
	s_waitcnt vmcnt(14)
	ds_write_b32 v78, v108
	s_waitcnt vmcnt(13)
	ds_write_b32 v80, v109
	s_waitcnt vmcnt(12)
	ds_write_b32 v82, v110
	s_waitcnt vmcnt(11)
	ds_write_b32 v84, v111
	s_waitcnt vmcnt(10)
	ds_write_b32 v86, v112
	s_waitcnt vmcnt(9)
	ds_write_b32 v88, v113
	s_waitcnt vmcnt(8)
	ds_write_b32 v90, v114
	s_waitcnt vmcnt(7)
	ds_write_b32 v92, v115
	s_waitcnt vmcnt(6)
	ds_write_b32 v94, v116
	s_waitcnt vmcnt(5)
	ds_write_b32 v96, v117
	s_waitcnt vmcnt(4)
	ds_write_b32 v98, v118
	s_waitcnt vmcnt(3)
	ds_write_b32 v100, v119
	s_waitcnt vmcnt(2)
	ds_write_b32 v102, v120
	s_waitcnt vmcnt(1)
	ds_write_b32 v104, v121
	s_waitcnt vmcnt(0)
	ds_write_b32 v106, v122
	s_cbranch_scc1 .LBB0_58
	s_waitcnt lgkmcnt(0)
	ds_read2_b32 v[48:49], v64 offset0:33 offset1:41
	ds_read2_b32 v[50:51], v64 offset1:8
	ds_read2_b32 v[52:53], v64 offset0:66 offset1:74
	ds_read2_b32 v[54:55], v64 offset0:99 offset1:107
	ds_read2_b32 v[56:57], v64 offset0:132 offset1:140
	ds_read2_b32 v[58:59], v64 offset0:165 offset1:173
	ds_read2_b32 v[60:61], v64 offset0:198 offset1:206
	ds_read2_b32 v[76:77], v64 offset0:231 offset1:239
	s_and_b32 s9, 0xffff, s9
	s_and_b32 s6, 0xffff, s8
	v_add_u32_e32 v80, s9, v63
	s_lshl_b32 s6, s6, 1
	v_ashrrev_i32_e32 v81, 31, v80
	v_lshl_add_u64 v[78:79], v[30:31], 0, s[6:7]
	v_lshlrev_b64 v[80:81], 11, v[80:81]
	s_waitcnt lgkmcnt(6)
	v_cvt_pk_bf16_f32 v44, v50, v48
	s_waitcnt lgkmcnt(4)
	v_cvt_pk_bf16_f32 v45, v52, v54
	s_waitcnt lgkmcnt(2)
	v_cvt_pk_bf16_f32 v46, v56, v58
	s_waitcnt lgkmcnt(0)
	v_cvt_pk_bf16_f32 v47, v60, v76
	v_lshl_add_u64 v[80:81], v[78:79], 0, v[80:81]
	v_add_u32_e32 v48, s9, v65
	global_store_dwordx4 v[80:81], v[44:47], off
	s_nop 1
	v_cvt_pk_bf16_f32 v44, v51, v49
	v_ashrrev_i32_e32 v49, 31, v48
	v_cvt_pk_bf16_f32 v45, v53, v55
	v_cvt_pk_bf16_f32 v46, v57, v59
	v_cvt_pk_bf16_f32 v47, v61, v77
	v_lshlrev_b64 v[48:49], 11, v[48:49]
	ds_read2_b32 v[50:51], v64 offset0:49 offset1:57
	ds_read2_b32 v[52:53], v64 offset0:16 offset1:24
	ds_read2_b32 v[54:55], v64 offset0:82 offset1:90
	ds_read2_b32 v[56:57], v64 offset0:115 offset1:123
	ds_read2_b32 v[58:59], v64 offset0:148 offset1:156
	ds_read2_b32 v[60:61], v64 offset0:181 offset1:189
	ds_read2_b32 v[76:77], v64 offset0:214 offset1:222
	ds_read2_b32 v[80:81], v64 offset0:247 offset1:255
	v_lshl_add_u64 v[48:49], v[78:79], 0, v[48:49]
	global_store_dwordx4 v[48:49], v[44:47], off
	v_add_u32_e32 v48, s9, v66
	v_ashrrev_i32_e32 v49, 31, v48
	v_lshlrev_b64 v[48:49], 11, v[48:49]
	s_waitcnt lgkmcnt(6)
	v_cvt_pk_bf16_f32 v44, v52, v50
	s_waitcnt lgkmcnt(4)
	v_cvt_pk_bf16_f32 v45, v54, v56
	s_waitcnt lgkmcnt(2)
	v_cvt_pk_bf16_f32 v46, v58, v60
	s_waitcnt lgkmcnt(0)
	v_cvt_pk_bf16_f32 v47, v76, v80
	v_lshl_add_u64 v[48:49], v[78:79], 0, v[48:49]
	global_store_dwordx4 v[48:49], v[44:47], off
	v_add_u32_e32 v48, s9, v67
	v_ashrrev_i32_e32 v49, 31, v48
	v_lshlrev_b64 v[48:49], 11, v[48:49]
	v_cvt_pk_bf16_f32 v44, v53, v51
	v_cvt_pk_bf16_f32 v45, v55, v57
	v_cvt_pk_bf16_f32 v46, v59, v61
	v_cvt_pk_bf16_f32 v47, v77, v81
	v_lshl_add_u64 v[48:49], v[78:79], 0, v[48:49]
	global_store_dwordx4 v[48:49], v[44:47], off
	s_waitcnt lgkmcnt(0)

; __device__ __forceinline__ void phase0(const P0Args& A, LAS unsigned char* lds, int gw, int NGW, int wave, int lane, int gt, int NGT) {
;     ...
;             const int ks = r / 96, cb = r % 96, col = cb * 64 + lane;
;             float acc[8];
; #pragma unroll
;             for (int b = 0; b < 8; ++b) acc[b] = 0.f;
;             for (int kk = 0; kk < 64; ++kk) {
;                 const int k = ks * 64 + kk; const float w = A.ada_w[(size_t)k * ADAW + col];
; #pragma unroll
;                 for (int b = 0; b < 8; ++b) acc[b] += A.c[b * D + k] * w;
;             }
;             float* adap = (float*)(A.ws + WS_ADAP);
; #pragma unroll
;             for (int b = 0; b < 8; ++b) adap[(size_t)(ks * 8 + b) * ADAW + col] = acc[b];
;             continue;
.LBB0_62:
	s_add_u32 s10, s8, s24
	s_addc_u32 s11, s9, s25
	global_load_dword v124, v[50:51], off nt
	v_lshl_add_u64 v[50:51], v[50:51], 0, s[98:99]
	global_load_dword v125, v[50:51], off nt
	v_lshl_add_u64 v[50:51], v[50:51], 0, s[98:99]
	global_load_dword v126, v[50:51], off nt
	v_lshl_add_u64 v[50:51], v[50:51], 0, s[98:99]
	global_load_dword v127, v[50:51], off nt
	v_lshl_add_u64 v[50:51], v[50:51], 0, s[98:99]
	global_load_dword v128, v[50:51], off nt
	v_lshl_add_u64 v[50:51], v[50:51], 0, s[98:99]
	global_load_dword v129, v[50:51], off nt
	v_lshl_add_u64 v[50:51], v[50:51], 0, s[98:99]
	global_load_dword v130, v[50:51], off nt
	v_lshl_add_u64 v[50:51], v[50:51], 0, s[98:99]
	global_load_dword v131, v[50:51], off nt
	v_lshl_add_u64 v[50:51], v[50:51], 0, s[98:99]
	global_load_dwordx4 v[132:135], v3, s[10:11]
	global_load_dwordx4 v[136:139], v68, s[10:11]
	global_load_dwordx4 v[140:143], v69, s[10:11]
	global_load_dwordx4 v[144:147], v70, s[10:11]
	global_load_dwordx4 v[148:151], v71, s[10:11]
	global_load_dwordx4 v[152:155], v72, s[10:11]
	global_load_dwordx4 v[156:159], v73, s[10:11]
	global_load_dwordx4 v[160:163], v74, s[10:11]
	global_load_dwordx4 v[164:167], v3, s[10:11] offset:16
	global_load_dwordx4 v[168:171], v68, s[10:11] offset:16
	global_load_dwordx4 v[172:175], v69, s[10:11] offset:16
	global_load_dwordx4 v[176:179], v70, s[10:11] offset:16
	global_load_dwordx4 v[180:183], v71, s[10:11] offset:16
	global_load_dwordx4 v[184:187], v72, s[10:11] offset:16
	global_load_dwordx4 v[188:191], v73, s[10:11] offset:16
	global_load_dwordx4 v[192:195], v74, s[10:11] offset:16
	s_add_u32 s24, s24, 32
	s_addc_u32 s25, s25, 0
	s_cmpk_eq_i32 s24, 0x100
	s_waitcnt vmcnt(8)
	v_fma_f32 v54, v124, v132, v54
	v_fma_f32 v55, v124, v136, v55
	v_fma_f32 v52, v124, v140, v52
	v_fma_f32 v53, v124, v144, v53
	v_fma_f32 v48, v124, v148, v48
	v_fma_f32 v49, v124, v152, v49
	v_fma_f32 v44, v124, v156, v44
	v_fma_f32 v45, v124, v160, v45
	v_fma_f32 v54, v125, v133, v54
	v_fma_f32 v55, v125, v137, v55
	v_fma_f32 v52, v125, v141, v52
	v_fma_f32 v53, v125, v145, v53
	v_fma_f32 v48, v125, v149, v48
	v_fma_f32 v49, v125, v153, v49
	v_fma_f32 v44, v125, v157, v44
	v_fma_f32 v45, v125, v161, v45
	v_fma_f32 v54, v126, v134, v54
	v_fma_f32 v55, v126, v138, v55
	v_fma_f32 v52, v126, v142, v52
	v_fma_f32 v53, v126, v146, v53
	v_fma_f32 v48, v126, v150, v48
	v_fma_f32 v49, v126, v154, v49
	v_fma_f32 v44, v126, v158, v44
	v_fma_f32 v45, v126, v162, v45
	v_fma_f32 v54, v127, v135, v54
	v_fma_f32 v55, v127, v139, v55
	v_fma_f32 v52, v127, v143, v52
	v_fma_f32 v53, v127, v147, v53
	v_fma_f32 v48, v127, v151, v48
	v_fma_f32 v49, v127, v155, v49
	v_fma_f32 v44, v127, v159, v44
	v_fma_f32 v45, v127, v163, v45
	s_waitcnt vmcnt(0)
	v_fma_f32 v54, v128, v164, v54
	v_fma_f32 v55, v128, v168, v55
	v_fma_f32 v52, v128, v172, v52
	v_fma_f32 v53, v128, v176, v53
	v_fma_f32 v48, v128, v180, v48
	v_fma_f32 v49, v128, v184, v49
	v_fma_f32 v44, v128, v188, v44
	v_fma_f32 v45, v128, v192, v45
	v_fma_f32 v54, v129, v165, v54
	v_fma_f32 v55, v129, v169, v55
	v_fma_f32 v52, v129, v173, v52
	v_fma_f32 v53, v129, v177, v53
	v_fma_f32 v48, v129, v181, v48
	v_fma_f32 v49, v129, v185, v49
	v_fma_f32 v44, v129, v189, v44
	v_fma_f32 v45, v129, v193, v45
	v_fma_f32 v54, v130, v166, v54
	v_fma_f32 v55, v130, v170, v55
	v_fma_f32 v52, v130, v174, v52
	v_fma_f32 v53, v130, v178, v53
	v_fma_f32 v48, v130, v182, v48
	v_fma_f32 v49, v130, v186, v49
	v_fma_f32 v44, v130, v190, v44
	v_fma_f32 v45, v130, v194, v45
	v_fma_f32 v54, v131, v167, v54
	v_fma_f32 v55, v131, v171, v55
	v_fma_f32 v52, v131, v175, v52
	v_fma_f32 v53, v131, v179, v53
	v_fma_f32 v48, v131, v183, v48
	v_fma_f32 v49, v131, v187, v49
	v_fma_f32 v44, v131, v191, v44
	v_fma_f32 v45, v131, v195, v45
	s_cbranch_scc0 .LBB0_62
	s_lshl_b32 s6, s6, 3
	v_lshl_add_u64 v[46:47], v[46:47], 2, s[4:5]
	v_mad_i64_i32 v[50:51], s[8:9], s6, v73, v[46:47]
	s_or_b32 s8, s6, 1
	global_store_dword v[50:51], v54, off
	v_mad_i64_i32 v[50:51], s[8:9], s8, v73, v[46:47]
	s_or_b32 s8, s6, 2
	global_store_dword v[50:51], v55, off
	v_mad_i64_i32 v[50:51], s[8:9], s8, v73, v[46:47]
	s_or_b32 s8, s6, 3
	global_store_dword v[50:51], v52, off
	v_mad_i64_i32 v[50:51], s[8:9], s8, v73, v[46:47]
	s_or_b32 s8, s6, 4
	global_store_dword v[50:51], v53, off
	v_mad_i64_i32 v[50:51], s[8:9], s8, v73, v[46:47]
	s_or_b32 s8, s6, 5
	global_store_dword v[50:51], v48, off
	v_mad_i64_i32 v[50:51], s[8:9], s8, v73, v[46:47]
	s_or_b32 s8, s6, 6
	s_or_b32 s6, s6, 7
	global_store_dword v[50:51], v49, off
	v_mad_i64_i32 v[48:49], s[8:9], s8, v73, v[46:47]
	v_mad_i64_i32 v[46:47], s[8:9], s6, v73, v[46:47]
	global_store_dword v[48:49], v44, off
	global_store_dword v[46:47], v45, off
	s_branch .LBB0_19
